# attention epilogue 2-byte H stores marked nt (on v37)
# speedup vs baseline: 1.0001x; 1.0001x over previous
; #define SBAR() __builtin_amdgcn_sched_barrier(0)
; __device__ __forceinline__ int crow(int r, int hi) { return (r & 3) + 8 * (r >> 2) + 4 * hi; }
; __device__ __forceinline__ void mla_unit(char* lds, const bf16_t* __restrict__ Qp, const bf16_t* __restrict__ Knp, const bf16_t* __restrict__ Vp, ...
;     ...
;   if (hi == 0) li_l[r32] = l_reg; asm volatile("s_waitcnt lgkmcnt(0)" ::: "memory");
;   float rli[16];
; #pragma unroll
;   for (int r = 0; r < 16; ++r) rli[r] = __builtin_amdgcn_rcpf(li_l[crow(r, hi)]);
;   { unsigned zr[16][4];
; #pragma unroll
;     for (int r = 0; r < 16; ++r) { const long trow = wid * QBLK + crow(r, hi);
; #pragma unroll
;       for (int d0 = 0; d0 < 4; ++d0) zr[r][d0] = Zp[trow * LDZ + d0 * 32 + r32]; }
;     asm volatile("s_waitcnt vmcnt(0)" ::: "memory"); SBAR();
.LBB0_235:
	s_or_b64 exec, exec, s[6:7]
	s_waitcnt lgkmcnt(0)
	ds_read_b128 v[66:69], v90
	ds_read_b128 v[70:73], v90 offset:32
	s_lshl_b32 s0, s38, 22
	s_and_b32 s0, s0, 0x3800000
	s_add_u32 s5, s90, s0
	s_waitcnt lgkmcnt(1)
	v_rcp_f32_e32 v171, v66
	v_rcp_f32_e32 v166, v67
	v_rcp_f32_e32 v161, v68
	v_rcp_f32_e32 v155, v69
	ds_read_b128 v[66:69], v90 offset:64
	s_addc_u32 s6, s91, 0
	s_lshl_b64 s[0:1], s[64:65], 9
	s_add_u32 s0, s5, s0
	s_addc_u32 s1, s6, s1
	s_lshl_b32 s5, s69, 8
	s_and_b32 s5, s5, 0x100
	s_add_u32 s6, s0, s5
	s_waitcnt lgkmcnt(0)
	v_rcp_f32_e32 v128, v66
	v_rcp_f32_e32 v122, v67
	v_rcp_f32_e32 v117, v68
	v_rcp_f32_e32 v111, v69
	ds_read_b128 v[66:69], v90 offset:96
	s_addc_u32 s7, s1, 0
	s_lshl_b32 s0, s38, 15
	s_add_u32 s0, s64, s0
	s_addc_u32 s1, s65, 0
	s_lshl_b64 s[0:1], s[0:1], 7
	s_add_u32 s40, s28, s0
	s_waitcnt lgkmcnt(0)
	v_rcp_f32_e32 v105, v66
	v_rcp_f32_e32 v103, v67
	v_or_b32_e32 v98, s39, v195
	v_lshlrev_b32_e32 v66, 1, v196
	v_mov_b32_e32 v67, v0
	s_addc_u32 s41, s29, s1
	v_rcp_f32_e32 v102, v68
	v_rcp_f32_e32 v1, v69
	v_lshl_add_u64 v[68:69], s[6:7], 0, v[66:67]
	s_mov_b64 s[0:1], 0x2000000
	v_ashrrev_i32_e32 v99, 31, v98
	v_lshl_add_u64 v[100:101], v[68:69], 0, s[0:1]
	v_lshlrev_b64 v[68:69], 9, v[98:99]
	v_or_b32_e32 v96, 1, v98
	v_lshl_add_u64 v[68:69], v[100:101], 0, v[68:69]
	v_ashrrev_i32_e32 v97, 31, v96
	global_load_ushort v180, v[68:69], off
	global_load_ushort v177, v[68:69], off offset:64
	global_load_ushort v176, v[68:69], off offset:128
	global_load_ushort v175, v[68:69], off offset:192
	v_lshlrev_b64 v[68:69], 9, v[96:97]
	v_or_b32_e32 v94, 2, v98
	v_lshl_add_u64 v[68:69], v[100:101], 0, v[68:69]
	v_ashrrev_i32_e32 v95, 31, v94
	global_load_ushort v174, v[68:69], off
	global_load_ushort v173, v[68:69], off offset:64
	global_load_ushort v172, v[68:69], off offset:128
	global_load_ushort v170, v[68:69], off offset:192
	v_lshlrev_b64 v[68:69], 9, v[94:95]
	v_or_b32_e32 v92, 3, v98
	v_lshl_add_u64 v[68:69], v[100:101], 0, v[68:69]
	v_ashrrev_i32_e32 v93, 31, v92
	global_load_ushort v169, v[68:69], off
	global_load_ushort v168, v[68:69], off offset:64
	global_load_ushort v167, v[68:69], off offset:128
	global_load_ushort v165, v[68:69], off offset:192
	v_lshlrev_b64 v[68:69], 9, v[92:93]
	v_or_b32_e32 v90, 8, v98
	v_lshl_add_u64 v[68:69], v[100:101], 0, v[68:69]
	v_ashrrev_i32_e32 v91, 31, v90
	global_load_ushort v164, v[68:69], off
	global_load_ushort v163, v[68:69], off offset:64
	global_load_ushort v162, v[68:69], off offset:128
	global_load_ushort v160, v[68:69], off offset:192
	v_lshlrev_b64 v[68:69], 9, v[90:91]
	v_or_b32_e32 v88, 9, v98
	v_lshl_add_u64 v[68:69], v[100:101], 0, v[68:69]
	v_ashrrev_i32_e32 v89, 31, v88
	global_load_ushort v159, v[68:69], off
	global_load_ushort v158, v[68:69], off offset:64
	global_load_ushort v157, v[68:69], off offset:128
	global_load_ushort v156, v[68:69], off offset:192
	v_lshlrev_b64 v[68:69], 9, v[88:89]
	v_or_b32_e32 v86, 10, v98
	v_lshl_add_u64 v[68:69], v[100:101], 0, v[68:69]
	v_ashrrev_i32_e32 v87, 31, v86
	global_load_ushort v154, v[68:69], off
	global_load_ushort v153, v[68:69], off offset:64
	global_load_ushort v152, v[68:69], off offset:128
	global_load_ushort v151, v[68:69], off offset:192
	v_lshlrev_b64 v[68:69], 9, v[86:87]
	v_or_b32_e32 v84, 11, v98
	v_lshl_add_u64 v[68:69], v[100:101], 0, v[68:69]
	v_ashrrev_i32_e32 v85, 31, v84
	global_load_ushort v149, v[68:69], off
	global_load_ushort v148, v[68:69], off offset:64
	global_load_ushort v147, v[68:69], off offset:128
	global_load_ushort v146, v[68:69], off offset:192
	v_lshlrev_b64 v[68:69], 9, v[84:85]
	v_or_b32_e32 v82, 16, v98
	v_lshl_add_u64 v[68:69], v[100:101], 0, v[68:69]
	v_ashrrev_i32_e32 v83, 31, v82
	global_load_ushort v145, v[68:69], off
	global_load_ushort v143, v[68:69], off offset:64
	global_load_ushort v142, v[68:69], off offset:128
	global_load_ushort v141, v[68:69], off offset:192
	v_lshlrev_b64 v[68:69], 9, v[82:83]
	v_or_b32_e32 v80, 17, v98
	v_lshl_add_u64 v[68:69], v[100:101], 0, v[68:69]
	v_ashrrev_i32_e32 v81, 31, v80
	global_load_ushort v140, v[68:69], off
	global_load_ushort v138, v[68:69], off offset:64
	global_load_ushort v137, v[68:69], off offset:128
	global_load_ushort v136, v[68:69], off offset:192
	v_lshlrev_b64 v[68:69], 9, v[80:81]
	v_or_b32_e32 v78, 18, v98
	v_lshl_add_u64 v[68:69], v[100:101], 0, v[68:69]
	v_ashrrev_i32_e32 v79, 31, v78
	global_load_ushort v135, v[68:69], off
	global_load_ushort v134, v[68:69], off offset:64
	global_load_ushort v132, v[68:69], off offset:128
	global_load_ushort v131, v[68:69], off offset:192
	v_lshlrev_b64 v[68:69], 9, v[78:79]
	v_or_b32_e32 v76, 19, v98
	v_lshl_add_u64 v[68:69], v[100:101], 0, v[68:69]
	v_ashrrev_i32_e32 v77, 31, v76
	global_load_ushort v130, v[68:69], off
	global_load_ushort v129, v[68:69], off offset:64
	global_load_ushort v127, v[68:69], off offset:128
	global_load_ushort v126, v[68:69], off offset:192
	v_lshlrev_b64 v[68:69], 9, v[76:77]
	v_or_b32_e32 v74, 24, v98
	v_lshl_add_u64 v[68:69], v[100:101], 0, v[68:69]
	v_ashrrev_i32_e32 v75, 31, v74
	v_rcp_f32_e32 v139, v72
	global_load_ushort v125, v[68:69], off
	global_load_ushort v124, v[68:69], off offset:64
	global_load_ushort v123, v[68:69], off offset:128
	global_load_ushort v121, v[68:69], off offset:192
	v_lshlrev_b64 v[68:69], 9, v[74:75]
	v_or_b32_e32 v72, 25, v98
	v_rcp_f32_e32 v133, v73
	v_lshl_add_u64 v[68:69], v[100:101], 0, v[68:69]
	v_ashrrev_i32_e32 v73, 31, v72
	v_rcp_f32_e32 v150, v70
	global_load_ushort v120, v[68:69], off
	global_load_ushort v119, v[68:69], off offset:64
	global_load_ushort v118, v[68:69], off offset:128
	global_load_ushort v116, v[68:69], off offset:192
	v_lshlrev_b64 v[68:69], 9, v[72:73]
	v_or_b32_e32 v70, 26, v98
	v_rcp_f32_e32 v144, v71
	v_lshl_add_u64 v[68:69], v[100:101], 0, v[68:69]
	v_ashrrev_i32_e32 v71, 31, v70
	global_load_ushort v115, v[68:69], off
	global_load_ushort v114, v[68:69], off offset:64
	global_load_ushort v113, v[68:69], off offset:128
	global_load_ushort v112, v[68:69], off offset:192
	v_lshlrev_b64 v[68:69], 9, v[70:71]
	v_lshl_add_u64 v[68:69], v[100:101], 0, v[68:69]
	global_load_ushort v110, v[68:69], off
	global_load_ushort v109, v[68:69], off offset:64
	global_load_ushort v108, v[68:69], off offset:128
	global_load_ushort v107, v[68:69], off offset:192
	v_or_b32_e32 v68, 27, v98
	v_ashrrev_i32_e32 v69, 31, v68
	v_lshlrev_b64 v[178:179], 9, v[68:69]
	v_lshl_add_u64 v[178:179], v[100:101], 0, v[178:179]
	global_load_ushort v106, v[178:179], off
	global_load_ushort v104, v[178:179], off offset:64
	global_load_ushort v101, v[178:179], off offset:128
	global_load_ushort v100, v[178:179], off offset:192
	s_waitcnt vmcnt(0)
; __device__ __forceinline__ float bf2f(unsigned h) { return __uint_as_float(h << 16); }
; __device__ __forceinline__ unsigned f2bf(float f) { unsigned u = __float_as_uint(f); return (u + 0x7fffu + ((u >> 16) & 1u)) >> 16; }
; __device__ __forceinline__ int crow(int r, int hi) { return (r & 3) + 8 * (r >> 2) + 4 * hi; }
; __device__ __forceinline__ void mla_unit(char* lds, const bf16_t* __restrict__ Qp, const bf16_t* __restrict__ Knp, const bf16_t* __restrict__ Vp, ...
;     ...
; #pragma unroll
;     for (int r = 0; r < 16; ++r) { const long trow = wid * QBLK + crow(r, hi);
; #pragma unroll
;       for (int d0 = 0; d0 < 4; ++d0) { const float z = bf2f(zr[r][d0]); const float v = o[d0][r] * rli[r];
;         const float g = v * z * __builtin_amdgcn_rcpf(1.f + __expf(-z));
;         Op[((size_t)(d0 >> 1) * M_TOK + trow) * 64 + (d0 & 1) * 32 + r32] = (bf16_t)f2bf(g); } } }
	s_waitcnt vmcnt(62)
	v_lshlrev_b32_e32 v178, 16, v180
	v_mul_f32_e32 v50, v50, v171
	v_mul_f32_e32 v50, v50, v178
	v_mul_f32_e32 v178, 0xbfb8aa3b, v178
	v_exp_f32_e32 v178, v178
	v_lshlrev_b64 v[98:99], 7, v[98:99]
	v_lshl_add_u64 v[98:99], s[40:41], 0, v[98:99]
	v_lshl_add_u64 v[98:99], v[98:99], 0, v[66:67]
	v_add_f32_e32 v178, 1.0, v178
	v_rcp_f32_e32 v178, v178
	v_mul_f32_e32 v34, v34, v171
	v_mul_f32_e32 v18, v18, v171
	v_mul_f32_e32 v2, v2, v171
	v_mul_f32_e32 v50, v50, v178
	v_bfe_u32 v178, v50, 16, 1
	v_add3_u32 v50, v50, v178, s63
	global_store_short_d16_hi v[98:99], v50, off nt
	v_lshlrev_b32_e32 v50, 16, v177
	v_mul_f32_e32 v34, v34, v50
	v_mul_f32_e32 v50, 0xbfb8aa3b, v50
	v_exp_f32_e32 v50, v50
	v_mul_f32_e32 v3, v3, v166
	v_mul_f32_e32 v4, v4, v161
	v_mul_f32_e32 v5, v5, v155
	v_add_f32_e32 v50, 1.0, v50
	v_rcp_f32_e32 v50, v50
	s_mov_b32 s74, s8
	v_mul_f32_e32 v34, v34, v50
	v_bfe_u32 v50, v34, 16, 1
	v_add3_u32 v34, v34, v50, s63
	global_store_short_d16_hi v[98:99], v34, off offset:64 nt
	s_waitcnt vmcnt(62)
	v_lshlrev_b32_e32 v34, 16, v176
	v_mul_f32_e32 v18, v18, v34
	v_mul_f32_e32 v34, 0xbfb8aa3b, v34
	v_exp_f32_e32 v34, v34
	v_add_co_u32_e32 v98, vcc, s93, v98
	v_add_f32_e32 v34, 1.0, v34
	v_rcp_f32_e32 v34, v34
	v_addc_co_u32_e32 v99, vcc, 0, v99, vcc
	v_mul_f32_e32 v18, v18, v34
	v_bfe_u32 v34, v18, 16, 1
	v_add3_u32 v18, v18, v34, s63
	global_store_short_d16_hi v[98:99], v18, off nt
	v_lshlrev_b32_e32 v18, 16, v175
	v_mul_f32_e32 v2, v2, v18
	v_mul_f32_e32 v18, 0xbfb8aa3b, v18
	v_exp_f32_e32 v18, v18
	s_nop 0
	v_add_f32_e32 v18, 1.0, v18
	v_rcp_f32_e32 v18, v18
	s_nop 0
	v_mul_f32_e32 v2, v2, v18
	v_bfe_u32 v18, v2, 16, 1
	v_add3_u32 v2, v2, v18, s63
	global_store_short_d16_hi v[98:99], v2, off offset:64 nt
	s_waitcnt vmcnt(62)
	v_lshlrev_b32_e32 v2, 16, v174
	v_mul_f32_e32 v18, v51, v166
	v_mul_f32_e32 v18, v18, v2
	v_mul_f32_e32 v2, 0xbfb8aa3b, v2
	v_exp_f32_e32 v2, v2
	v_lshlrev_b64 v[50:51], 7, v[96:97]
	v_lshl_add_u64 v[50:51], s[40:41], 0, v[50:51]
	v_lshl_add_u64 v[50:51], v[50:51], 0, v[66:67]
	v_add_f32_e32 v2, 1.0, v2
	v_rcp_f32_e32 v2, v2
	s_nop 0
	v_mul_f32_e32 v2, v18, v2
	v_bfe_u32 v18, v2, 16, 1
	v_add3_u32 v2, v2, v18, s63
	global_store_short_d16_hi v[50:51], v2, off nt
	v_lshlrev_b32_e32 v2, 16, v173
	v_mul_f32_e32 v18, v35, v166
	v_mul_f32_e32 v18, v18, v2
	v_mul_f32_e32 v2, 0xbfb8aa3b, v2
	v_exp_f32_e32 v2, v2
	s_nop 0
	v_add_f32_e32 v2, 1.0, v2
	v_rcp_f32_e32 v2, v2
	s_nop 0
	v_mul_f32_e32 v2, v18, v2
	v_bfe_u32 v18, v2, 16, 1
	v_add3_u32 v2, v2, v18, s63
	global_store_short_d16_hi v[50:51], v2, off offset:64 nt
	s_waitcnt vmcnt(62)
	v_lshlrev_b32_e32 v2, 16, v172
	v_mul_f32_e32 v18, v19, v166
	v_mul_f32_e32 v18, v18, v2
	v_mul_f32_e32 v2, 0xbfb8aa3b, v2
	v_exp_f32_e32 v2, v2
	s_nop 0
	v_add_f32_e32 v2, 1.0, v2
	v_rcp_f32_e32 v2, v2
	s_nop 0
	v_mul_f32_e32 v2, v18, v2
	v_bfe_u32 v18, v2, 16, 1
	v_add3_u32 v2, v2, v18, s63
	v_add_co_u32_e32 v18, vcc, s93, v50
	s_nop 1
	v_addc_co_u32_e32 v19, vcc, 0, v51, vcc
	global_store_short_d16_hi v[18:19], v2, off nt
	v_lshlrev_b32_e32 v2, 16, v170
	v_mul_f32_e32 v3, v3, v2
	v_mul_f32_e32 v2, 0xbfb8aa3b, v2
	v_exp_f32_e32 v2, v2
	s_nop 0
	v_add_f32_e32 v2, 1.0, v2
	v_rcp_f32_e32 v2, v2
	s_nop 0
	v_mul_f32_e32 v2, v3, v2
	v_bfe_u32 v3, v2, 16, 1
	v_add3_u32 v2, v2, v3, s63
	global_store_short_d16_hi v[18:19], v2, off offset:64 nt
	s_waitcnt vmcnt(62)
	v_lshlrev_b32_e32 v2, 16, v169
	v_mul_f32_e32 v3, v52, v161
	v_mul_f32_e32 v3, v3, v2
	v_mul_f32_e32 v2, 0xbfb8aa3b, v2
	v_exp_f32_e32 v2, v2
	v_mul_f32_e32 v19, v36, v161
	v_add_f32_e32 v2, 1.0, v2
	v_rcp_f32_e32 v2, v2
	s_nop 0
	v_mul_f32_e32 v2, v3, v2
	v_bfe_u32 v3, v2, 16, 1
	v_add3_u32 v18, v2, v3, s63
	v_lshlrev_b64 v[2:3], 7, v[94:95]
	v_lshl_add_u64 v[2:3], s[40:41], 0, v[2:3]
	v_lshl_add_u64 v[2:3], v[2:3], 0, v[66:67]
	global_store_short_d16_hi v[2:3], v18, off nt
	v_lshlrev_b32_e32 v18, 16, v168
	v_mul_f32_e32 v19, v19, v18
	v_mul_f32_e32 v18, 0xbfb8aa3b, v18
	v_exp_f32_e32 v18, v18
	s_nop 0
	v_add_f32_e32 v18, 1.0, v18
	v_rcp_f32_e32 v18, v18
	s_nop 0
	v_mul_f32_e32 v18, v19, v18
	v_bfe_u32 v19, v18, 16, 1
	v_add3_u32 v18, v18, v19, s63
	global_store_short_d16_hi v[2:3], v18, off offset:64 nt
	s_waitcnt vmcnt(62)
	v_lshlrev_b32_e32 v18, 16, v167
	v_mul_f32_e32 v19, v20, v161
	v_mul_f32_e32 v19, v19, v18
	v_mul_f32_e32 v18, 0xbfb8aa3b, v18
	v_exp_f32_e32 v18, v18
	v_add_co_u32_e32 v2, vcc, s93, v2
	v_add_f32_e32 v18, 1.0, v18
	v_rcp_f32_e32 v18, v18
	v_addc_co_u32_e32 v3, vcc, 0, v3, vcc
	v_mul_f32_e32 v18, v19, v18
	v_bfe_u32 v19, v18, 16, 1
	v_add3_u32 v18, v18, v19, s63
	global_store_short_d16_hi v[2:3], v18, off nt
	v_lshlrev_b32_e32 v18, 16, v165
	v_mul_f32_e32 v4, v4, v18
	v_mul_f32_e32 v18, 0xbfb8aa3b, v18
	v_exp_f32_e32 v18, v18
	s_nop 0
	v_add_f32_e32 v18, 1.0, v18
	v_rcp_f32_e32 v18, v18
	s_nop 0
	v_mul_f32_e32 v4, v4, v18
	v_bfe_u32 v18, v4, 16, 1
	v_add3_u32 v4, v4, v18, s63
	global_store_short_d16_hi v[2:3], v4, off offset:64 nt
	s_waitcnt vmcnt(62)
	v_lshlrev_b32_e32 v2, 16, v164
	v_mul_f32_e32 v3, v53, v155
	v_mul_f32_e32 v3, v3, v2
	v_mul_f32_e32 v2, 0xbfb8aa3b, v2
	v_exp_f32_e32 v2, v2
	v_mul_f32_e32 v18, v37, v155
	v_add_f32_e32 v2, 1.0, v2
	v_rcp_f32_e32 v2, v2
	s_nop 0
	v_mul_f32_e32 v2, v3, v2
	v_bfe_u32 v3, v2, 16, 1
	v_add3_u32 v4, v2, v3, s63
	v_lshlrev_b64 v[2:3], 7, v[92:93]
	v_lshl_add_u64 v[2:3], s[40:41], 0, v[2:3]
	v_lshl_add_u64 v[2:3], v[2:3], 0, v[66:67]
	global_store_short_d16_hi v[2:3], v4, off nt
	v_lshlrev_b32_e32 v4, 16, v163
	v_mul_f32_e32 v18, v18, v4
	v_mul_f32_e32 v4, 0xbfb8aa3b, v4
	v_exp_f32_e32 v4, v4
	s_nop 0
	v_add_f32_e32 v4, 1.0, v4
	v_rcp_f32_e32 v4, v4
	s_nop 0
	v_mul_f32_e32 v4, v18, v4
	v_bfe_u32 v18, v4, 16, 1
	v_add3_u32 v4, v4, v18, s63
	global_store_short_d16_hi v[2:3], v4, off offset:64 nt
	s_waitcnt vmcnt(62)
; __device__ __forceinline__ float bf2f(unsigned h) { return __uint_as_float(h << 16); }
; __device__ __forceinline__ unsigned f2bf(float f) { unsigned u = __float_as_uint(f); return (u + 0x7fffu + ((u >> 16) & 1u)) >> 16; }
; __device__ __forceinline__ int crow(int r, int hi) { return (r & 3) + 8 * (r >> 2) + 4 * hi; }
; __device__ __forceinline__ void mla_unit(char* lds, const bf16_t* __restrict__ Qp, const bf16_t* __restrict__ Knp, const bf16_t* __restrict__ Vp, ...
;     ...
; #pragma unroll
;     for (int r = 0; r < 16; ++r) { const long trow = wid * QBLK + crow(r, hi);
; #pragma unroll
;       for (int d0 = 0; d0 < 4; ++d0) { const float z = bf2f(zr[r][d0]); const float v = o[d0][r] * rli[r];
;         const float g = v * z * __builtin_amdgcn_rcpf(1.f + __expf(-z));
;         Op[((size_t)(d0 >> 1) * M_TOK + trow) * 64 + (d0 & 1) * 32 + r32] = (bf16_t)f2bf(g); } } }
	v_lshlrev_b32_e32 v4, 16, v162
	v_mul_f32_e32 v18, v21, v155
	v_mul_f32_e32 v18, v18, v4
	v_mul_f32_e32 v4, 0xbfb8aa3b, v4
	v_exp_f32_e32 v4, v4
	v_add_co_u32_e32 v2, vcc, s93, v2
	v_add_f32_e32 v4, 1.0, v4
	v_rcp_f32_e32 v4, v4
	v_addc_co_u32_e32 v3, vcc, 0, v3, vcc
	v_mul_f32_e32 v4, v18, v4
	v_bfe_u32 v18, v4, 16, 1
	v_add3_u32 v4, v4, v18, s63
	global_store_short_d16_hi v[2:3], v4, off nt
	v_lshlrev_b32_e32 v4, 16, v160
	v_mul_f32_e32 v5, v5, v4
	v_mul_f32_e32 v4, 0xbfb8aa3b, v4
	v_exp_f32_e32 v4, v4
	s_nop 0
	v_add_f32_e32 v4, 1.0, v4
	v_rcp_f32_e32 v4, v4
	s_nop 0
	v_mul_f32_e32 v4, v5, v4
	v_bfe_u32 v5, v4, 16, 1
	v_add3_u32 v4, v4, v5, s63
	global_store_short_d16_hi v[2:3], v4, off offset:64 nt
	s_waitcnt vmcnt(62)
	v_lshlrev_b32_e32 v2, 16, v159
	v_mul_f32_e32 v3, v54, v150
	v_mul_f32_e32 v3, v3, v2
	v_mul_f32_e32 v2, 0xbfb8aa3b, v2
	v_exp_f32_e32 v2, v2
	v_mul_f32_e32 v5, v38, v150
	v_add_f32_e32 v2, 1.0, v2
	v_rcp_f32_e32 v2, v2
	s_nop 0
	v_mul_f32_e32 v2, v3, v2
	v_bfe_u32 v3, v2, 16, 1
	v_add3_u32 v4, v2, v3, s63
	v_lshlrev_b64 v[2:3], 7, v[90:91]
	v_lshl_add_u64 v[2:3], s[40:41], 0, v[2:3]
	v_lshl_add_u64 v[2:3], v[2:3], 0, v[66:67]
	global_store_short_d16_hi v[2:3], v4, off nt
	v_lshlrev_b32_e32 v4, 16, v158
	v_mul_f32_e32 v5, v5, v4
	v_mul_f32_e32 v4, 0xbfb8aa3b, v4
	v_exp_f32_e32 v4, v4
	s_nop 0
	v_add_f32_e32 v4, 1.0, v4
	v_rcp_f32_e32 v4, v4
	s_nop 0
	v_mul_f32_e32 v4, v5, v4
	v_bfe_u32 v5, v4, 16, 1
	v_add3_u32 v4, v4, v5, s63
	global_store_short_d16_hi v[2:3], v4, off offset:64 nt
	s_waitcnt vmcnt(62)
	v_lshlrev_b32_e32 v4, 16, v157
	v_mul_f32_e32 v5, v22, v150
	v_mul_f32_e32 v5, v5, v4
	v_mul_f32_e32 v4, 0xbfb8aa3b, v4
	v_exp_f32_e32 v4, v4
	v_add_co_u32_e32 v2, vcc, s93, v2
	v_add_f32_e32 v4, 1.0, v4
	v_rcp_f32_e32 v4, v4
	v_addc_co_u32_e32 v3, vcc, 0, v3, vcc
	v_mul_f32_e32 v4, v5, v4
	v_bfe_u32 v5, v4, 16, 1
	v_add3_u32 v4, v4, v5, s63
	global_store_short_d16_hi v[2:3], v4, off nt
	v_lshlrev_b32_e32 v4, 16, v156
	v_mul_f32_e32 v5, v6, v150
	v_mul_f32_e32 v5, v5, v4
	v_mul_f32_e32 v4, 0xbfb8aa3b, v4
	v_exp_f32_e32 v4, v4
	s_nop 0
	v_add_f32_e32 v4, 1.0, v4
	v_rcp_f32_e32 v4, v4
	s_nop 0
	v_mul_f32_e32 v4, v5, v4
	v_bfe_u32 v5, v4, 16, 1
	v_add3_u32 v4, v4, v5, s63
	global_store_short_d16_hi v[2:3], v4, off offset:64 nt
	s_waitcnt vmcnt(62)
	v_lshlrev_b32_e32 v2, 16, v154
	v_mul_f32_e32 v3, v55, v144
	v_mul_f32_e32 v3, v3, v2
	v_mul_f32_e32 v2, 0xbfb8aa3b, v2
	v_exp_f32_e32 v2, v2
	v_mul_f32_e32 v5, v39, v144
	v_add_f32_e32 v2, 1.0, v2
	v_rcp_f32_e32 v2, v2
	s_nop 0
	v_mul_f32_e32 v2, v3, v2
	v_bfe_u32 v3, v2, 16, 1
	v_add3_u32 v4, v2, v3, s63
	v_lshlrev_b64 v[2:3], 7, v[88:89]
	v_lshl_add_u64 v[2:3], s[40:41], 0, v[2:3]
	v_lshl_add_u64 v[2:3], v[2:3], 0, v[66:67]
	global_store_short_d16_hi v[2:3], v4, off nt
	v_lshlrev_b32_e32 v4, 16, v153
	v_mul_f32_e32 v5, v5, v4
	v_mul_f32_e32 v4, 0xbfb8aa3b, v4
	v_exp_f32_e32 v4, v4
	s_nop 0
	v_add_f32_e32 v4, 1.0, v4
	v_rcp_f32_e32 v4, v4
	s_nop 0
	v_mul_f32_e32 v4, v5, v4
	v_bfe_u32 v5, v4, 16, 1
	v_add3_u32 v4, v4, v5, s63
	global_store_short_d16_hi v[2:3], v4, off offset:64 nt
	s_waitcnt vmcnt(62)
	v_lshlrev_b32_e32 v4, 16, v152
	v_mul_f32_e32 v5, v23, v144
	v_mul_f32_e32 v5, v5, v4
	v_mul_f32_e32 v4, 0xbfb8aa3b, v4
	v_exp_f32_e32 v4, v4
	v_add_co_u32_e32 v2, vcc, s93, v2
	v_add_f32_e32 v4, 1.0, v4
	v_rcp_f32_e32 v4, v4
	v_addc_co_u32_e32 v3, vcc, 0, v3, vcc
	v_mul_f32_e32 v4, v5, v4
	v_bfe_u32 v5, v4, 16, 1
	v_add3_u32 v4, v4, v5, s63
	global_store_short_d16_hi v[2:3], v4, off nt
	v_lshlrev_b32_e32 v4, 16, v151
	v_mul_f32_e32 v5, v7, v144
	v_mul_f32_e32 v5, v5, v4
	v_mul_f32_e32 v4, 0xbfb8aa3b, v4
	v_exp_f32_e32 v4, v4
	s_nop 0
	v_add_f32_e32 v4, 1.0, v4
	v_rcp_f32_e32 v4, v4
	s_nop 0
	v_mul_f32_e32 v4, v5, v4
	v_bfe_u32 v5, v4, 16, 1
	v_add3_u32 v4, v4, v5, s63
	global_store_short_d16_hi v[2:3], v4, off offset:64 nt
	s_waitcnt vmcnt(62)
	v_lshlrev_b32_e32 v2, 16, v149
	v_mul_f32_e32 v3, v56, v139
	v_mul_f32_e32 v3, v3, v2
	v_mul_f32_e32 v2, 0xbfb8aa3b, v2
	v_exp_f32_e32 v2, v2
	v_mul_f32_e32 v5, v40, v139
	v_add_f32_e32 v2, 1.0, v2
	v_rcp_f32_e32 v2, v2
	s_nop 0
	v_mul_f32_e32 v2, v3, v2
	v_bfe_u32 v3, v2, 16, 1
	v_add3_u32 v4, v2, v3, s63
	v_lshlrev_b64 v[2:3], 7, v[86:87]
	v_lshl_add_u64 v[2:3], s[40:41], 0, v[2:3]
	v_lshl_add_u64 v[2:3], v[2:3], 0, v[66:67]
	global_store_short_d16_hi v[2:3], v4, off nt
	v_lshlrev_b32_e32 v4, 16, v148
	v_mul_f32_e32 v5, v5, v4
	v_mul_f32_e32 v4, 0xbfb8aa3b, v4
	v_exp_f32_e32 v4, v4
	s_nop 0
	v_add_f32_e32 v4, 1.0, v4
	v_rcp_f32_e32 v4, v4
	s_nop 0
	v_mul_f32_e32 v4, v5, v4
	v_bfe_u32 v5, v4, 16, 1
	v_add3_u32 v4, v4, v5, s63
	global_store_short_d16_hi v[2:3], v4, off offset:64 nt
	s_waitcnt vmcnt(62)
	v_lshlrev_b32_e32 v4, 16, v147
	v_mul_f32_e32 v5, v24, v139
	v_mul_f32_e32 v5, v5, v4
	v_mul_f32_e32 v4, 0xbfb8aa3b, v4
	v_exp_f32_e32 v4, v4
	v_add_co_u32_e32 v2, vcc, s93, v2
	v_add_f32_e32 v4, 1.0, v4
	v_rcp_f32_e32 v4, v4
	v_addc_co_u32_e32 v3, vcc, 0, v3, vcc
	v_mul_f32_e32 v4, v5, v4
	v_bfe_u32 v5, v4, 16, 1
	v_add3_u32 v4, v4, v5, s63
	global_store_short_d16_hi v[2:3], v4, off nt
	v_lshlrev_b32_e32 v4, 16, v146
	v_mul_f32_e32 v5, v8, v139
	v_mul_f32_e32 v5, v5, v4
	v_mul_f32_e32 v4, 0xbfb8aa3b, v4
	v_exp_f32_e32 v4, v4
	s_nop 0
	v_add_f32_e32 v4, 1.0, v4
	v_rcp_f32_e32 v4, v4
	s_nop 0
	v_mul_f32_e32 v4, v5, v4
	v_bfe_u32 v5, v4, 16, 1
	v_add3_u32 v4, v4, v5, s63
	global_store_short_d16_hi v[2:3], v4, off offset:64 nt
	s_waitcnt vmcnt(62)
; __device__ __forceinline__ float bf2f(unsigned h) { return __uint_as_float(h << 16); }
; __device__ __forceinline__ unsigned f2bf(float f) { unsigned u = __float_as_uint(f); return (u + 0x7fffu + ((u >> 16) & 1u)) >> 16; }
; __device__ __forceinline__ int crow(int r, int hi) { return (r & 3) + 8 * (r >> 2) + 4 * hi; }
; __device__ __forceinline__ void mla_unit(char* lds, const bf16_t* __restrict__ Qp, const bf16_t* __restrict__ Knp, const bf16_t* __restrict__ Vp, ...
;     ...
; #pragma unroll
;     for (int r = 0; r < 16; ++r) { const long trow = wid * QBLK + crow(r, hi);
; #pragma unroll
;       for (int d0 = 0; d0 < 4; ++d0) { const float z = bf2f(zr[r][d0]); const float v = o[d0][r] * rli[r];
;         const float g = v * z * __builtin_amdgcn_rcpf(1.f + __expf(-z));
;         Op[((size_t)(d0 >> 1) * M_TOK + trow) * 64 + (d0 & 1) * 32 + r32] = (bf16_t)f2bf(g); } } }
	v_lshlrev_b32_e32 v2, 16, v145
	v_mul_f32_e32 v3, v57, v133
	v_mul_f32_e32 v3, v3, v2
	v_mul_f32_e32 v2, 0xbfb8aa3b, v2
	v_exp_f32_e32 v2, v2
	v_mul_f32_e32 v5, v41, v133
	v_add_f32_e32 v2, 1.0, v2
	v_rcp_f32_e32 v2, v2
	s_nop 0
	v_mul_f32_e32 v2, v3, v2
	v_bfe_u32 v3, v2, 16, 1
	v_add3_u32 v4, v2, v3, s63
	v_lshlrev_b64 v[2:3], 7, v[84:85]
	v_lshl_add_u64 v[2:3], s[40:41], 0, v[2:3]
	v_lshl_add_u64 v[2:3], v[2:3], 0, v[66:67]
	global_store_short_d16_hi v[2:3], v4, off nt
	v_lshlrev_b32_e32 v4, 16, v143
	v_mul_f32_e32 v5, v5, v4
	v_mul_f32_e32 v4, 0xbfb8aa3b, v4
	v_exp_f32_e32 v4, v4
	s_nop 0
	v_add_f32_e32 v4, 1.0, v4
	v_rcp_f32_e32 v4, v4
	s_nop 0
	v_mul_f32_e32 v4, v5, v4
	v_bfe_u32 v5, v4, 16, 1
	v_add3_u32 v4, v4, v5, s63
	global_store_short_d16_hi v[2:3], v4, off offset:64 nt
	s_waitcnt vmcnt(62)
	v_lshlrev_b32_e32 v4, 16, v142
	v_mul_f32_e32 v5, v25, v133
	v_mul_f32_e32 v5, v5, v4
	v_mul_f32_e32 v4, 0xbfb8aa3b, v4
	v_exp_f32_e32 v4, v4
	v_add_co_u32_e32 v2, vcc, s93, v2
	v_add_f32_e32 v4, 1.0, v4
	v_rcp_f32_e32 v4, v4
	v_addc_co_u32_e32 v3, vcc, 0, v3, vcc
	v_mul_f32_e32 v4, v5, v4
	v_bfe_u32 v5, v4, 16, 1
	v_add3_u32 v4, v4, v5, s63
	global_store_short_d16_hi v[2:3], v4, off nt
	v_lshlrev_b32_e32 v4, 16, v141
	v_mul_f32_e32 v5, v9, v133
	v_mul_f32_e32 v5, v5, v4
	v_mul_f32_e32 v4, 0xbfb8aa3b, v4
	v_exp_f32_e32 v4, v4
	s_nop 0
	v_add_f32_e32 v4, 1.0, v4
	v_rcp_f32_e32 v4, v4
	s_nop 0
	v_mul_f32_e32 v4, v5, v4
	v_bfe_u32 v5, v4, 16, 1
	v_add3_u32 v4, v4, v5, s63
	global_store_short_d16_hi v[2:3], v4, off offset:64 nt
	s_waitcnt vmcnt(62)
	v_lshlrev_b32_e32 v2, 16, v140
	v_mul_f32_e32 v3, v58, v128
	v_mul_f32_e32 v3, v3, v2
	v_mul_f32_e32 v2, 0xbfb8aa3b, v2
	v_exp_f32_e32 v2, v2
	v_mul_f32_e32 v5, v42, v128
	v_add_f32_e32 v2, 1.0, v2
	v_rcp_f32_e32 v2, v2
	s_nop 0
	v_mul_f32_e32 v2, v3, v2
	v_bfe_u32 v3, v2, 16, 1
	v_add3_u32 v4, v2, v3, s63
	v_lshlrev_b64 v[2:3], 7, v[82:83]
	v_lshl_add_u64 v[2:3], s[40:41], 0, v[2:3]
	v_lshl_add_u64 v[2:3], v[2:3], 0, v[66:67]
	global_store_short_d16_hi v[2:3], v4, off nt
	v_lshlrev_b32_e32 v4, 16, v138
	v_mul_f32_e32 v5, v5, v4
	v_mul_f32_e32 v4, 0xbfb8aa3b, v4
	v_exp_f32_e32 v4, v4
	s_nop 0
	v_add_f32_e32 v4, 1.0, v4
	v_rcp_f32_e32 v4, v4
	s_nop 0
	v_mul_f32_e32 v4, v5, v4
	v_bfe_u32 v5, v4, 16, 1
	v_add3_u32 v4, v4, v5, s63
	global_store_short_d16_hi v[2:3], v4, off offset:64 nt
	s_waitcnt vmcnt(62)
	v_lshlrev_b32_e32 v4, 16, v137
	v_mul_f32_e32 v5, v26, v128
	v_mul_f32_e32 v5, v5, v4
	v_mul_f32_e32 v4, 0xbfb8aa3b, v4
	v_exp_f32_e32 v4, v4
	v_add_co_u32_e32 v2, vcc, s93, v2
	v_add_f32_e32 v4, 1.0, v4
	v_rcp_f32_e32 v4, v4
	v_addc_co_u32_e32 v3, vcc, 0, v3, vcc
	v_mul_f32_e32 v4, v5, v4
	v_bfe_u32 v5, v4, 16, 1
	v_add3_u32 v4, v4, v5, s63
	global_store_short_d16_hi v[2:3], v4, off nt
	v_lshlrev_b32_e32 v4, 16, v136
	v_mul_f32_e32 v5, v10, v128
	v_mul_f32_e32 v5, v5, v4
	v_mul_f32_e32 v4, 0xbfb8aa3b, v4
	v_exp_f32_e32 v4, v4
	s_nop 0
	v_add_f32_e32 v4, 1.0, v4
	v_rcp_f32_e32 v4, v4
	s_nop 0
	v_mul_f32_e32 v4, v5, v4
	v_bfe_u32 v5, v4, 16, 1
	v_add3_u32 v4, v4, v5, s63
	global_store_short_d16_hi v[2:3], v4, off offset:64 nt
	s_waitcnt vmcnt(62)
	v_lshlrev_b32_e32 v2, 16, v135
	v_mul_f32_e32 v3, v59, v122
	v_mul_f32_e32 v3, v3, v2
	v_mul_f32_e32 v2, 0xbfb8aa3b, v2
	v_exp_f32_e32 v2, v2
	v_mul_f32_e32 v5, v43, v122
	v_add_f32_e32 v2, 1.0, v2
	v_rcp_f32_e32 v2, v2
	s_nop 0
	v_mul_f32_e32 v2, v3, v2
	v_bfe_u32 v3, v2, 16, 1
	v_add3_u32 v4, v2, v3, s63
	v_lshlrev_b64 v[2:3], 7, v[80:81]
	v_lshl_add_u64 v[2:3], s[40:41], 0, v[2:3]
	v_lshl_add_u64 v[2:3], v[2:3], 0, v[66:67]
	global_store_short_d16_hi v[2:3], v4, off nt
	v_lshlrev_b32_e32 v4, 16, v134
	v_mul_f32_e32 v5, v5, v4
	v_mul_f32_e32 v4, 0xbfb8aa3b, v4
	v_exp_f32_e32 v4, v4
	s_nop 0
	v_add_f32_e32 v4, 1.0, v4
	v_rcp_f32_e32 v4, v4
	s_nop 0
	v_mul_f32_e32 v4, v5, v4
	v_bfe_u32 v5, v4, 16, 1
	v_add3_u32 v4, v4, v5, s63
	global_store_short_d16_hi v[2:3], v4, off offset:64 nt
	s_waitcnt vmcnt(62)
	v_lshlrev_b32_e32 v4, 16, v132
	v_mul_f32_e32 v5, v27, v122
	v_mul_f32_e32 v5, v5, v4
	v_mul_f32_e32 v4, 0xbfb8aa3b, v4
	v_exp_f32_e32 v4, v4
	v_add_co_u32_e32 v2, vcc, s93, v2
	v_add_f32_e32 v4, 1.0, v4
	v_rcp_f32_e32 v4, v4
	v_addc_co_u32_e32 v3, vcc, 0, v3, vcc
	v_mul_f32_e32 v4, v5, v4
	v_bfe_u32 v5, v4, 16, 1
	v_add3_u32 v4, v4, v5, s63
	global_store_short_d16_hi v[2:3], v4, off nt
	v_lshlrev_b32_e32 v4, 16, v131
	v_mul_f32_e32 v5, v11, v122
	v_mul_f32_e32 v5, v5, v4
	v_mul_f32_e32 v4, 0xbfb8aa3b, v4
	v_exp_f32_e32 v4, v4
	s_nop 0
	v_add_f32_e32 v4, 1.0, v4
	v_rcp_f32_e32 v4, v4
	s_nop 0
	v_mul_f32_e32 v4, v5, v4
	v_bfe_u32 v5, v4, 16, 1
	v_add3_u32 v4, v4, v5, s63
	global_store_short_d16_hi v[2:3], v4, off offset:64 nt
	s_waitcnt vmcnt(62)
	v_lshlrev_b32_e32 v2, 16, v130
	v_mul_f32_e32 v3, v60, v117
	v_mul_f32_e32 v3, v3, v2
	v_mul_f32_e32 v2, 0xbfb8aa3b, v2
	v_exp_f32_e32 v2, v2
	v_mul_f32_e32 v5, v44, v117
	v_add_f32_e32 v2, 1.0, v2
	v_rcp_f32_e32 v2, v2
	s_nop 0
	v_mul_f32_e32 v2, v3, v2
	v_bfe_u32 v3, v2, 16, 1
	v_add3_u32 v4, v2, v3, s63
	v_lshlrev_b64 v[2:3], 7, v[78:79]
	v_lshl_add_u64 v[2:3], s[40:41], 0, v[2:3]
	v_lshl_add_u64 v[2:3], v[2:3], 0, v[66:67]
	global_store_short_d16_hi v[2:3], v4, off nt
	v_lshlrev_b32_e32 v4, 16, v129
	v_mul_f32_e32 v5, v5, v4
	v_mul_f32_e32 v4, 0xbfb8aa3b, v4
	v_exp_f32_e32 v4, v4
	s_nop 0
	v_add_f32_e32 v4, 1.0, v4
	v_rcp_f32_e32 v4, v4
	s_nop 0
	v_mul_f32_e32 v4, v5, v4
	v_bfe_u32 v5, v4, 16, 1
	v_add3_u32 v4, v4, v5, s63
	global_store_short_d16_hi v[2:3], v4, off offset:64 nt
	s_waitcnt vmcnt(62)
; __device__ __forceinline__ float bf2f(unsigned h) { return __uint_as_float(h << 16); }
; __device__ __forceinline__ unsigned f2bf(float f) { unsigned u = __float_as_uint(f); return (u + 0x7fffu + ((u >> 16) & 1u)) >> 16; }
; __device__ __forceinline__ int crow(int r, int hi) { return (r & 3) + 8 * (r >> 2) + 4 * hi; }
; __device__ __forceinline__ void mla_unit(char* lds, const bf16_t* __restrict__ Qp, const bf16_t* __restrict__ Knp, const bf16_t* __restrict__ Vp, ...
;     ...
; #pragma unroll
;     for (int r = 0; r < 16; ++r) { const long trow = wid * QBLK + crow(r, hi);
; #pragma unroll
;       for (int d0 = 0; d0 < 4; ++d0) { const float z = bf2f(zr[r][d0]); const float v = o[d0][r] * rli[r];
;         const float g = v * z * __builtin_amdgcn_rcpf(1.f + __expf(-z));
;         Op[((size_t)(d0 >> 1) * M_TOK + trow) * 64 + (d0 & 1) * 32 + r32] = (bf16_t)f2bf(g); } } }
	v_lshlrev_b32_e32 v4, 16, v127
	v_mul_f32_e32 v5, v28, v117
	v_mul_f32_e32 v5, v5, v4
	v_mul_f32_e32 v4, 0xbfb8aa3b, v4
	v_exp_f32_e32 v4, v4
	v_add_co_u32_e32 v2, vcc, s93, v2
	v_add_f32_e32 v4, 1.0, v4
	v_rcp_f32_e32 v4, v4
	v_addc_co_u32_e32 v3, vcc, 0, v3, vcc
	v_mul_f32_e32 v4, v5, v4
	v_bfe_u32 v5, v4, 16, 1
	v_add3_u32 v4, v4, v5, s63
	global_store_short_d16_hi v[2:3], v4, off nt
	v_lshlrev_b32_e32 v4, 16, v126
	v_mul_f32_e32 v5, v12, v117
	v_mul_f32_e32 v5, v5, v4
	v_mul_f32_e32 v4, 0xbfb8aa3b, v4
	v_exp_f32_e32 v4, v4
	s_nop 0
	v_add_f32_e32 v4, 1.0, v4
	v_rcp_f32_e32 v4, v4
	s_nop 0
	v_mul_f32_e32 v4, v5, v4
	v_bfe_u32 v5, v4, 16, 1
	v_add3_u32 v4, v4, v5, s63
	global_store_short_d16_hi v[2:3], v4, off offset:64 nt
	s_waitcnt vmcnt(62)
	v_lshlrev_b32_e32 v2, 16, v125
	v_mul_f32_e32 v3, v61, v111
	v_mul_f32_e32 v3, v3, v2
	v_mul_f32_e32 v2, 0xbfb8aa3b, v2
	v_exp_f32_e32 v2, v2
	v_mul_f32_e32 v5, v45, v111
	v_add_f32_e32 v2, 1.0, v2
	v_rcp_f32_e32 v2, v2
	s_nop 0
	v_mul_f32_e32 v2, v3, v2
	v_bfe_u32 v3, v2, 16, 1
	v_add3_u32 v4, v2, v3, s63
	v_lshlrev_b64 v[2:3], 7, v[76:77]
	v_lshl_add_u64 v[2:3], s[40:41], 0, v[2:3]
	v_lshl_add_u64 v[2:3], v[2:3], 0, v[66:67]
	global_store_short_d16_hi v[2:3], v4, off nt
	v_lshlrev_b32_e32 v4, 16, v124
	v_mul_f32_e32 v5, v5, v4
	v_mul_f32_e32 v4, 0xbfb8aa3b, v4
	v_exp_f32_e32 v4, v4
	s_nop 0
	v_add_f32_e32 v4, 1.0, v4
	v_rcp_f32_e32 v4, v4
	s_nop 0
	v_mul_f32_e32 v4, v5, v4
	v_bfe_u32 v5, v4, 16, 1
	v_add3_u32 v4, v4, v5, s63
	global_store_short_d16_hi v[2:3], v4, off offset:64 nt
	s_waitcnt vmcnt(62)
	v_lshlrev_b32_e32 v4, 16, v123
	v_mul_f32_e32 v5, v29, v111
	v_mul_f32_e32 v5, v5, v4
	v_mul_f32_e32 v4, 0xbfb8aa3b, v4
	v_exp_f32_e32 v4, v4
	v_add_co_u32_e32 v2, vcc, s93, v2
	v_add_f32_e32 v4, 1.0, v4
	v_rcp_f32_e32 v4, v4
	v_addc_co_u32_e32 v3, vcc, 0, v3, vcc
	v_mul_f32_e32 v4, v5, v4
	v_bfe_u32 v5, v4, 16, 1
	v_add3_u32 v4, v4, v5, s63
	global_store_short_d16_hi v[2:3], v4, off nt
	v_lshlrev_b32_e32 v4, 16, v121
	v_mul_f32_e32 v5, v13, v111
	v_mul_f32_e32 v5, v5, v4
	v_mul_f32_e32 v4, 0xbfb8aa3b, v4
	v_exp_f32_e32 v4, v4
	s_nop 0
	v_add_f32_e32 v4, 1.0, v4
	v_rcp_f32_e32 v4, v4
	s_nop 0
	v_mul_f32_e32 v4, v5, v4
	v_bfe_u32 v5, v4, 16, 1
	v_add3_u32 v4, v4, v5, s63
	global_store_short_d16_hi v[2:3], v4, off offset:64 nt
	s_waitcnt vmcnt(62)
	v_lshlrev_b32_e32 v2, 16, v120
	v_mul_f32_e32 v3, v62, v105
	v_mul_f32_e32 v3, v3, v2
	v_mul_f32_e32 v2, 0xbfb8aa3b, v2
	v_exp_f32_e32 v2, v2
	v_mul_f32_e32 v5, v46, v105
	v_add_f32_e32 v2, 1.0, v2
	v_rcp_f32_e32 v2, v2
	s_nop 0
	v_mul_f32_e32 v2, v3, v2
	v_bfe_u32 v3, v2, 16, 1
	v_add3_u32 v4, v2, v3, s63
	v_lshlrev_b64 v[2:3], 7, v[74:75]
	v_lshl_add_u64 v[2:3], s[40:41], 0, v[2:3]
	v_lshl_add_u64 v[2:3], v[2:3], 0, v[66:67]
	global_store_short_d16_hi v[2:3], v4, off nt
	v_lshlrev_b32_e32 v4, 16, v119
	v_mul_f32_e32 v5, v5, v4
	v_mul_f32_e32 v4, 0xbfb8aa3b, v4
	v_exp_f32_e32 v4, v4
	s_nop 0
	v_add_f32_e32 v4, 1.0, v4
	v_rcp_f32_e32 v4, v4
	s_nop 0
	v_mul_f32_e32 v4, v5, v4
	v_bfe_u32 v5, v4, 16, 1
	v_add3_u32 v4, v4, v5, s63
	global_store_short_d16_hi v[2:3], v4, off offset:64 nt
	s_waitcnt vmcnt(62)
	v_lshlrev_b32_e32 v4, 16, v118
	v_mul_f32_e32 v5, v30, v105
	v_mul_f32_e32 v5, v5, v4
	v_mul_f32_e32 v4, 0xbfb8aa3b, v4
	v_exp_f32_e32 v4, v4
	v_add_co_u32_e32 v2, vcc, s93, v2
	v_add_f32_e32 v4, 1.0, v4
	v_rcp_f32_e32 v4, v4
	v_addc_co_u32_e32 v3, vcc, 0, v3, vcc
	v_mul_f32_e32 v4, v5, v4
	v_bfe_u32 v5, v4, 16, 1
	v_add3_u32 v4, v4, v5, s63
	global_store_short_d16_hi v[2:3], v4, off nt
	v_lshlrev_b32_e32 v4, 16, v116
	v_mul_f32_e32 v5, v14, v105
	v_mul_f32_e32 v5, v5, v4
	v_mul_f32_e32 v4, 0xbfb8aa3b, v4
	v_exp_f32_e32 v4, v4
	s_nop 0
	v_add_f32_e32 v4, 1.0, v4
	v_rcp_f32_e32 v4, v4
	s_nop 0
	v_mul_f32_e32 v4, v5, v4
	v_bfe_u32 v5, v4, 16, 1
	v_add3_u32 v4, v4, v5, s63
	global_store_short_d16_hi v[2:3], v4, off offset:64 nt
	s_waitcnt vmcnt(62)
	v_lshlrev_b32_e32 v2, 16, v115
	v_mul_f32_e32 v3, v63, v103
	v_mul_f32_e32 v3, v3, v2
	v_mul_f32_e32 v2, 0xbfb8aa3b, v2
	v_exp_f32_e32 v2, v2
	v_mul_f32_e32 v5, v47, v103
	v_add_f32_e32 v2, 1.0, v2
	v_rcp_f32_e32 v2, v2
	s_nop 0
	v_mul_f32_e32 v2, v3, v2
	v_bfe_u32 v3, v2, 16, 1
	v_add3_u32 v4, v2, v3, s63
	v_lshlrev_b64 v[2:3], 7, v[72:73]
	v_lshl_add_u64 v[2:3], s[40:41], 0, v[2:3]
	v_lshl_add_u64 v[2:3], v[2:3], 0, v[66:67]
	global_store_short_d16_hi v[2:3], v4, off nt
	v_lshlrev_b32_e32 v4, 16, v114
	v_mul_f32_e32 v5, v5, v4
	v_mul_f32_e32 v4, 0xbfb8aa3b, v4
	v_exp_f32_e32 v4, v4
	s_nop 0
	v_add_f32_e32 v4, 1.0, v4
	v_rcp_f32_e32 v4, v4
	s_nop 0
	v_mul_f32_e32 v4, v5, v4
	v_bfe_u32 v5, v4, 16, 1
	v_add3_u32 v4, v4, v5, s63
	global_store_short_d16_hi v[2:3], v4, off offset:64 nt
	s_waitcnt vmcnt(62)
; __device__ __forceinline__ float bf2f(unsigned h) { return __uint_as_float(h << 16); }
; __device__ __forceinline__ unsigned f2bf(float f) { unsigned u = __float_as_uint(f); return (u + 0x7fffu + ((u >> 16) & 1u)) >> 16; }
; __device__ __forceinline__ int crow(int r, int hi) { return (r & 3) + 8 * (r >> 2) + 4 * hi; }
; __device__ __forceinline__ void mla_unit(char* lds, const bf16_t* __restrict__ Qp, const bf16_t* __restrict__ Knp, const bf16_t* __restrict__ Vp, ...
;     ...
; #pragma unroll
;     for (int r = 0; r < 16; ++r) { const long trow = wid * QBLK + crow(r, hi);
; #pragma unroll
;       for (int d0 = 0; d0 < 4; ++d0) { const float z = bf2f(zr[r][d0]); const float v = o[d0][r] * rli[r];
;         const float g = v * z * __builtin_amdgcn_rcpf(1.f + __expf(-z));
;         Op[((size_t)(d0 >> 1) * M_TOK + trow) * 64 + (d0 & 1) * 32 + r32] = (bf16_t)f2bf(g); } } }
;   asm volatile("s_waitcnt vmcnt(0) lgkmcnt(0)\n\ts_barrier" ::: "memory");
	v_lshlrev_b32_e32 v4, 16, v113
	v_mul_f32_e32 v5, v31, v103
	v_mul_f32_e32 v5, v5, v4
	v_mul_f32_e32 v4, 0xbfb8aa3b, v4
	v_exp_f32_e32 v4, v4
	v_add_co_u32_e32 v2, vcc, s93, v2
	v_add_f32_e32 v4, 1.0, v4
	v_rcp_f32_e32 v4, v4
	v_addc_co_u32_e32 v3, vcc, 0, v3, vcc
	v_mul_f32_e32 v4, v5, v4
	v_bfe_u32 v5, v4, 16, 1
	v_add3_u32 v4, v4, v5, s63
	global_store_short_d16_hi v[2:3], v4, off nt
	v_lshlrev_b32_e32 v4, 16, v112
	v_mul_f32_e32 v5, v15, v103
	v_mul_f32_e32 v5, v5, v4
	v_mul_f32_e32 v4, 0xbfb8aa3b, v4
	v_exp_f32_e32 v4, v4
	s_nop 0
	v_add_f32_e32 v4, 1.0, v4
	v_rcp_f32_e32 v4, v4
	s_nop 0
	v_mul_f32_e32 v4, v5, v4
	v_bfe_u32 v5, v4, 16, 1
	v_add3_u32 v4, v4, v5, s63
	global_store_short_d16_hi v[2:3], v4, off offset:64 nt
	s_waitcnt vmcnt(62)
	v_lshlrev_b32_e32 v2, 16, v110
	v_mul_f32_e32 v3, v64, v102
	v_mul_f32_e32 v3, v3, v2
	v_mul_f32_e32 v2, 0xbfb8aa3b, v2
	v_exp_f32_e32 v2, v2
	v_mul_f32_e32 v5, v48, v102
	v_add_f32_e32 v2, 1.0, v2
	v_rcp_f32_e32 v2, v2
	s_nop 0
	v_mul_f32_e32 v2, v3, v2
	v_bfe_u32 v3, v2, 16, 1
	v_add3_u32 v4, v2, v3, s63
	v_lshlrev_b64 v[2:3], 7, v[70:71]
	v_lshl_add_u64 v[2:3], s[40:41], 0, v[2:3]
	v_lshl_add_u64 v[2:3], v[2:3], 0, v[66:67]
	global_store_short_d16_hi v[2:3], v4, off nt
	v_lshlrev_b32_e32 v4, 16, v109
	v_mul_f32_e32 v5, v5, v4
	v_mul_f32_e32 v4, 0xbfb8aa3b, v4
	v_exp_f32_e32 v4, v4
	s_nop 0
	v_add_f32_e32 v4, 1.0, v4
	v_rcp_f32_e32 v4, v4
	s_nop 0
	v_mul_f32_e32 v4, v5, v4
	v_bfe_u32 v5, v4, 16, 1
	v_add3_u32 v4, v4, v5, s63
	global_store_short_d16_hi v[2:3], v4, off offset:64 nt
	s_waitcnt vmcnt(62)
	v_lshlrev_b32_e32 v4, 16, v108
	v_mul_f32_e32 v5, v32, v102
	v_mul_f32_e32 v5, v5, v4
	v_mul_f32_e32 v4, 0xbfb8aa3b, v4
	v_exp_f32_e32 v4, v4
	v_add_co_u32_e32 v2, vcc, s93, v2
	v_add_f32_e32 v4, 1.0, v4
	v_rcp_f32_e32 v4, v4
	v_addc_co_u32_e32 v3, vcc, 0, v3, vcc
	v_mul_f32_e32 v4, v5, v4
	v_bfe_u32 v5, v4, 16, 1
	v_add3_u32 v4, v4, v5, s63
	global_store_short_d16_hi v[2:3], v4, off nt
	v_lshlrev_b32_e32 v4, 16, v107
	v_mul_f32_e32 v5, v16, v102
	v_mul_f32_e32 v5, v5, v4
	v_mul_f32_e32 v4, 0xbfb8aa3b, v4
	v_exp_f32_e32 v4, v4
	s_nop 0
	v_add_f32_e32 v4, 1.0, v4
	v_rcp_f32_e32 v4, v4
	s_nop 0
	v_mul_f32_e32 v4, v5, v4
	v_bfe_u32 v5, v4, 16, 1
	v_add3_u32 v4, v4, v5, s63
	global_store_short_d16_hi v[2:3], v4, off offset:64 nt
	s_waitcnt vmcnt(62)
	v_lshlrev_b32_e32 v2, 16, v106
	v_mul_f32_e32 v3, v65, v1
	v_mul_f32_e32 v3, v3, v2
	v_mul_f32_e32 v2, 0xbfb8aa3b, v2
	v_exp_f32_e32 v2, v2
	v_mul_f32_e32 v5, v49, v1
	v_add_f32_e32 v2, 1.0, v2
	v_rcp_f32_e32 v2, v2
	s_nop 0
	v_mul_f32_e32 v2, v3, v2
	v_bfe_u32 v3, v2, 16, 1
	v_add3_u32 v4, v2, v3, s63
	v_lshlrev_b64 v[2:3], 7, v[68:69]
	v_lshl_add_u64 v[2:3], s[40:41], 0, v[2:3]
	v_lshl_add_u64 v[2:3], v[2:3], 0, v[66:67]
	global_store_short_d16_hi v[2:3], v4, off nt
	v_lshlrev_b32_e32 v4, 16, v104
	v_mul_f32_e32 v5, v5, v4
	v_mul_f32_e32 v4, 0xbfb8aa3b, v4
	v_exp_f32_e32 v4, v4
	s_nop 0
	v_add_f32_e32 v4, 1.0, v4
	v_rcp_f32_e32 v4, v4
	s_nop 0
	v_mul_f32_e32 v4, v5, v4
	v_bfe_u32 v5, v4, 16, 1
	v_add3_u32 v4, v4, v5, s63
	global_store_short_d16_hi v[2:3], v4, off offset:64 nt
	s_waitcnt vmcnt(62)
	v_lshlrev_b32_e32 v4, 16, v101
	v_mul_f32_e32 v5, v33, v1
	v_mul_f32_e32 v5, v5, v4
	v_mul_f32_e32 v4, 0xbfb8aa3b, v4
	v_exp_f32_e32 v4, v4
	v_add_co_u32_e32 v2, vcc, s93, v2
	v_mul_f32_e32 v1, v17, v1
	v_add_f32_e32 v4, 1.0, v4
	v_rcp_f32_e32 v4, v4
	v_addc_co_u32_e32 v3, vcc, 0, v3, vcc
	s_and_b64 vcc, exec, s[42:43]
	v_mul_f32_e32 v4, v5, v4
	v_bfe_u32 v5, v4, 16, 1
	v_add3_u32 v4, v4, v5, s63
	global_store_short_d16_hi v[2:3], v4, off nt
	v_lshlrev_b32_e32 v4, 16, v100
	v_mul_f32_e32 v1, v1, v4
	v_mul_f32_e32 v4, 0xbfb8aa3b, v4
	v_exp_f32_e32 v4, v4
	s_nop 0
	v_add_f32_e32 v4, 1.0, v4
	v_rcp_f32_e32 v4, v4
	s_nop 0
	v_mul_f32_e32 v1, v1, v4
	v_bfe_u32 v4, v1, 16, 1
	v_add3_u32 v1, v1, v4, s63
	global_store_short_d16_hi v[2:3], v1, off offset:64 nt
	s_setprio 0
	s_waitcnt vmcnt(0) lgkmcnt(0)
	s_barrier
	s_cbranch_vccnz .LBB0_271

; #define SBAR() __builtin_amdgcn_sched_barrier(0)
; __device__ __forceinline__ int crow(int r, int hi) { return (r & 3) + 8 * (r >> 2) + 4 * hi; }
; __device__ __forceinline__ void na_unit3(char* lds, const bf16_t* __restrict__ Qp, const bf16_t* __restrict__ Knp, const bf16_t* __restrict__ Vp, ...
;     ...
;   if (hi == 0) li_l[r32] = l_reg; asm volatile("s_waitcnt lgkmcnt(0)" ::: "memory");
;   float rli[16];
; #pragma unroll
;   for (int r = 0; r < 16; ++r) rli[r] = __builtin_amdgcn_rcpf(li_l[crow(r, hi)]);
;   { unsigned zr[16][4];
; #pragma unroll
;     for (int r = 0; r < 16; ++r) { const long trow = wid * QBLK + crow(r, hi);
; #pragma unroll
;       for (int d0 = 0; d0 < 4; ++d0) zr[r][d0] = Zp[trow * LDZ + d0 * 32 + r32]; }
;     asm volatile("s_waitcnt vmcnt(0)" ::: "memory"); SBAR();
.LBB0_275:
	s_or_b64 exec, exec, s[6:7]
	s_waitcnt lgkmcnt(0)
	v_lshl_add_u32 v1, v222, 4, s26
	ds_read_b128 v[2:5], v1
	ds_read_b128 v[6:9], v1 offset:32
	s_lshl_b64 s[0:1], s[82:83], 1
	s_add_u32 s6, s81, s0
	s_addc_u32 s7, s84, s1
	s_waitcnt lgkmcnt(1)
	v_rcp_f32_e32 v171, v2
	v_rcp_f32_e32 v166, v3
	v_rcp_f32_e32 v161, v4
	v_rcp_f32_e32 v155, v5
	ds_read_b128 v[2:5], v1 offset:64
	s_lshl_b32 s0, s77, 15
	s_add_u32 s0, s34, s0
	s_addc_u32 s1, s35, 0
	s_lshl_b64 s[0:1], s[0:1], 7
	s_waitcnt lgkmcnt(0)
	v_rcp_f32_e32 v128, v2
	v_rcp_f32_e32 v122, v3
	v_rcp_f32_e32 v117, v4
	v_rcp_f32_e32 v111, v5
	ds_read_b128 v[2:5], v1 offset:96
	s_add_u32 s34, s28, s0
	v_lshl_or_b32 v98, v222, 2, s80
	s_addc_u32 s35, s29, s1
	s_mov_b64 s[0:1], 0xc000000
	s_waitcnt lgkmcnt(0)
	v_rcp_f32_e32 v105, v2
	v_rcp_f32_e32 v103, v3
	v_lshlrev_b32_e32 v2, 1, v221
	v_mov_b32_e32 v3, v0
	v_rcp_f32_e32 v102, v4
	v_rcp_f32_e32 v1, v5
	v_lshl_add_u64 v[4:5], s[6:7], 0, v[2:3]
	v_ashrrev_i32_e32 v99, 31, v98
	v_lshl_add_u64 v[100:101], v[4:5], 0, s[0:1]
	v_lshlrev_b64 v[4:5], 9, v[98:99]
	v_or_b32_e32 v96, 1, v98
	v_lshl_add_u64 v[4:5], v[100:101], 0, v[4:5]
	v_ashrrev_i32_e32 v97, 31, v96
	global_load_ushort v180, v[4:5], off
	global_load_ushort v177, v[4:5], off offset:64
	global_load_ushort v176, v[4:5], off offset:128
	global_load_ushort v175, v[4:5], off offset:192
	v_lshlrev_b64 v[4:5], 9, v[96:97]
	v_or_b32_e32 v94, 2, v98
	v_lshl_add_u64 v[4:5], v[100:101], 0, v[4:5]
	v_ashrrev_i32_e32 v95, 31, v94
	global_load_ushort v174, v[4:5], off
	global_load_ushort v173, v[4:5], off offset:64
	global_load_ushort v172, v[4:5], off offset:128
	global_load_ushort v170, v[4:5], off offset:192
	v_lshlrev_b64 v[4:5], 9, v[94:95]
	v_or_b32_e32 v92, 3, v98
	v_lshl_add_u64 v[4:5], v[100:101], 0, v[4:5]
	v_ashrrev_i32_e32 v93, 31, v92
	global_load_ushort v169, v[4:5], off
	global_load_ushort v168, v[4:5], off offset:64
	global_load_ushort v167, v[4:5], off offset:128
	global_load_ushort v165, v[4:5], off offset:192
	v_lshlrev_b64 v[4:5], 9, v[92:93]
	v_or_b32_e32 v90, 8, v98
	v_lshl_add_u64 v[4:5], v[100:101], 0, v[4:5]
	v_ashrrev_i32_e32 v91, 31, v90
	global_load_ushort v164, v[4:5], off
	global_load_ushort v163, v[4:5], off offset:64
	global_load_ushort v162, v[4:5], off offset:128
	global_load_ushort v160, v[4:5], off offset:192
	v_lshlrev_b64 v[4:5], 9, v[90:91]
	v_or_b32_e32 v88, 9, v98
	v_lshl_add_u64 v[4:5], v[100:101], 0, v[4:5]
	v_ashrrev_i32_e32 v89, 31, v88
	global_load_ushort v159, v[4:5], off
	global_load_ushort v158, v[4:5], off offset:64
	global_load_ushort v157, v[4:5], off offset:128
	global_load_ushort v156, v[4:5], off offset:192
	v_lshlrev_b64 v[4:5], 9, v[88:89]
	v_or_b32_e32 v86, 10, v98
	v_lshl_add_u64 v[4:5], v[100:101], 0, v[4:5]
	v_ashrrev_i32_e32 v87, 31, v86
	global_load_ushort v154, v[4:5], off
	global_load_ushort v153, v[4:5], off offset:64
	global_load_ushort v152, v[4:5], off offset:128
	global_load_ushort v151, v[4:5], off offset:192
	v_lshlrev_b64 v[4:5], 9, v[86:87]
	v_or_b32_e32 v84, 11, v98
	v_lshl_add_u64 v[4:5], v[100:101], 0, v[4:5]
	v_ashrrev_i32_e32 v85, 31, v84
	global_load_ushort v150, v[4:5], off
	global_load_ushort v148, v[4:5], off offset:64
	global_load_ushort v147, v[4:5], off offset:128
	global_load_ushort v146, v[4:5], off offset:192
	v_lshlrev_b64 v[4:5], 9, v[84:85]
	v_or_b32_e32 v82, 16, v98
	v_lshl_add_u64 v[4:5], v[100:101], 0, v[4:5]
	v_ashrrev_i32_e32 v83, 31, v82
	global_load_ushort v145, v[4:5], off
	global_load_ushort v143, v[4:5], off offset:64
	global_load_ushort v142, v[4:5], off offset:128
	global_load_ushort v141, v[4:5], off offset:192
	v_lshlrev_b64 v[4:5], 9, v[82:83]
	v_or_b32_e32 v80, 17, v98
	v_lshl_add_u64 v[4:5], v[100:101], 0, v[4:5]
	v_ashrrev_i32_e32 v81, 31, v80
	global_load_ushort v140, v[4:5], off
	global_load_ushort v138, v[4:5], off offset:64
	global_load_ushort v137, v[4:5], off offset:128
	global_load_ushort v136, v[4:5], off offset:192
	v_lshlrev_b64 v[4:5], 9, v[80:81]
	v_or_b32_e32 v14, 18, v98
	v_lshl_add_u64 v[4:5], v[100:101], 0, v[4:5]
	v_ashrrev_i32_e32 v15, 31, v14
	global_load_ushort v135, v[4:5], off
	global_load_ushort v134, v[4:5], off offset:64
	global_load_ushort v132, v[4:5], off offset:128
	global_load_ushort v131, v[4:5], off offset:192
	v_lshlrev_b64 v[4:5], 9, v[14:15]
	v_or_b32_e32 v12, 19, v98
	v_lshl_add_u64 v[4:5], v[100:101], 0, v[4:5]
	v_ashrrev_i32_e32 v13, 31, v12
	global_load_ushort v130, v[4:5], off
	global_load_ushort v129, v[4:5], off offset:64
	global_load_ushort v127, v[4:5], off offset:128
	global_load_ushort v126, v[4:5], off offset:192
	v_lshlrev_b64 v[4:5], 9, v[12:13]
	v_or_b32_e32 v10, 24, v98
	v_lshl_add_u64 v[4:5], v[100:101], 0, v[4:5]
	v_ashrrev_i32_e32 v11, 31, v10
	v_rcp_f32_e32 v139, v8
	global_load_ushort v125, v[4:5], off
	global_load_ushort v124, v[4:5], off offset:64
	global_load_ushort v123, v[4:5], off offset:128
	global_load_ushort v121, v[4:5], off offset:192
	v_lshlrev_b64 v[4:5], 9, v[10:11]
	v_or_b32_e32 v8, 25, v98
	v_rcp_f32_e32 v133, v9
	v_lshl_add_u64 v[4:5], v[100:101], 0, v[4:5]
	v_ashrrev_i32_e32 v9, 31, v8
	v_rcp_f32_e32 v149, v6
	global_load_ushort v120, v[4:5], off
	global_load_ushort v119, v[4:5], off offset:64
	global_load_ushort v118, v[4:5], off offset:128
	global_load_ushort v116, v[4:5], off offset:192
	v_lshlrev_b64 v[4:5], 9, v[8:9]
	v_or_b32_e32 v6, 26, v98
	v_rcp_f32_e32 v144, v7
	v_lshl_add_u64 v[4:5], v[100:101], 0, v[4:5]
	v_ashrrev_i32_e32 v7, 31, v6
	global_load_ushort v115, v[4:5], off
	global_load_ushort v114, v[4:5], off offset:64
	global_load_ushort v113, v[4:5], off offset:128
	global_load_ushort v112, v[4:5], off offset:192
	v_lshlrev_b64 v[4:5], 9, v[6:7]
	v_lshl_add_u64 v[4:5], v[100:101], 0, v[4:5]
	global_load_ushort v110, v[4:5], off
	global_load_ushort v109, v[4:5], off offset:64
	global_load_ushort v108, v[4:5], off offset:128
	global_load_ushort v107, v[4:5], off offset:192
	v_or_b32_e32 v4, 27, v98
	v_ashrrev_i32_e32 v5, 31, v4
	v_lshlrev_b64 v[178:179], 9, v[4:5]
	v_lshl_add_u64 v[178:179], v[100:101], 0, v[178:179]
	global_load_ushort v106, v[178:179], off
	global_load_ushort v104, v[178:179], off offset:64
	global_load_ushort v101, v[178:179], off offset:128
	global_load_ushort v100, v[178:179], off offset:192
	s_waitcnt vmcnt(0)
; __device__ __forceinline__ float bf2f(unsigned h) { return __uint_as_float(h << 16); }
; __device__ __forceinline__ unsigned f2bf(float f) { unsigned u = __float_as_uint(f); return (u + 0x7fffu + ((u >> 16) & 1u)) >> 16; }
; __device__ __forceinline__ int crow(int r, int hi) { return (r & 3) + 8 * (r >> 2) + 4 * hi; }
; __device__ __forceinline__ void na_unit3(char* lds, const bf16_t* __restrict__ Qp, const bf16_t* __restrict__ Knp, const bf16_t* __restrict__ Vp, ...
;     ...
;     for (int r = 0; r < 16; ++r) { const long trow = wid * QBLK + crow(r, hi);
; #pragma unroll
;       for (int d0 = 0; d0 < 4; ++d0) { const float z = bf2f(zr[r][d0]); const float v = o[d0][r] * rli[r];
;         const float g = v * z * __builtin_amdgcn_rcpf(1.f + __expf(-z));
;         Op[((size_t)(d0 >> 1) * M_TOK + trow) * 64 + (d0 & 1) * 32 + r32] = (bf16_t)f2bf(g); } } }
	s_waitcnt vmcnt(62)
	v_lshlrev_b32_e32 v178, 16, v180
	v_mul_f32_e32 v64, v64, v171
	v_mul_f32_e32 v64, v64, v178
	v_mul_f32_e32 v178, 0xbfb8aa3b, v178
	v_exp_f32_e32 v178, v178
	v_lshlrev_b64 v[98:99], 7, v[98:99]
	v_lshl_add_u64 v[98:99], s[34:35], 0, v[98:99]
	v_lshl_add_u64 v[98:99], v[98:99], 0, v[2:3]
	v_add_f32_e32 v178, 1.0, v178
	v_rcp_f32_e32 v178, v178
	v_mul_f32_e32 v48, v48, v171
	v_mul_f32_e32 v32, v32, v171
	v_mul_f32_e32 v16, v16, v171
	v_mul_f32_e32 v64, v64, v178
	v_bfe_u32 v178, v64, 16, 1
	v_add3_u32 v64, v64, v178, s63
	global_store_short_d16_hi v[98:99], v64, off nt
	v_lshlrev_b32_e32 v64, 16, v177
	v_mul_f32_e32 v48, v48, v64
	v_mul_f32_e32 v64, 0xbfb8aa3b, v64
	v_exp_f32_e32 v64, v64
	v_mul_f32_e32 v17, v17, v166
	v_mul_f32_e32 v18, v18, v161
	v_mul_f32_e32 v19, v19, v155
	v_add_f32_e32 v64, 1.0, v64
	v_rcp_f32_e32 v64, v64
	v_lshlrev_b64 v[14:15], 7, v[14:15]
	v_lshl_add_u64 v[14:15], s[34:35], 0, v[14:15]
	v_lshl_add_u64 v[14:15], v[14:15], 0, v[2:3]
	v_mul_f32_e32 v48, v48, v64
	v_bfe_u32 v64, v48, 16, 1
	v_add3_u32 v48, v48, v64, s63
	global_store_short_d16_hi v[98:99], v48, off offset:64 nt
	s_waitcnt vmcnt(62)
	v_lshlrev_b32_e32 v48, 16, v176
	v_mul_f32_e32 v32, v32, v48
	v_mul_f32_e32 v48, 0xbfb8aa3b, v48
	v_exp_f32_e32 v48, v48
	v_add_co_u32_e32 v98, vcc, s93, v98
	v_lshlrev_b64 v[12:13], 7, v[12:13]
	v_add_f32_e32 v48, 1.0, v48
	v_rcp_f32_e32 v48, v48
	v_addc_co_u32_e32 v99, vcc, 0, v99, vcc
	v_lshl_add_u64 v[12:13], s[34:35], 0, v[12:13]
	v_mul_f32_e32 v32, v32, v48
	v_bfe_u32 v48, v32, 16, 1
	v_add3_u32 v32, v32, v48, s63
	global_store_short_d16_hi v[98:99], v32, off nt
	v_lshlrev_b32_e32 v32, 16, v175
	v_mul_f32_e32 v16, v16, v32
	v_mul_f32_e32 v32, 0xbfb8aa3b, v32
	v_exp_f32_e32 v32, v32
	v_lshl_add_u64 v[12:13], v[12:13], 0, v[2:3]
	v_lshlrev_b64 v[10:11], 7, v[10:11]
	v_lshl_add_u64 v[10:11], s[34:35], 0, v[10:11]
	v_add_f32_e32 v32, 1.0, v32
	v_rcp_f32_e32 v32, v32
	v_lshl_add_u64 v[10:11], v[10:11], 0, v[2:3]
	v_lshlrev_b64 v[8:9], 7, v[8:9]
	v_lshl_add_u64 v[8:9], s[34:35], 0, v[8:9]
	v_mul_f32_e32 v16, v16, v32
	v_bfe_u32 v32, v16, 16, 1
	v_add3_u32 v16, v16, v32, s63
	global_store_short_d16_hi v[98:99], v16, off offset:64 nt
	s_waitcnt vmcnt(62)
	v_lshlrev_b32_e32 v16, 16, v174
	v_mul_f32_e32 v32, v65, v166
	v_mul_f32_e32 v32, v32, v16
	v_mul_f32_e32 v16, 0xbfb8aa3b, v16
	v_exp_f32_e32 v16, v16
	v_lshlrev_b64 v[64:65], 7, v[96:97]
	v_lshl_add_u64 v[64:65], s[34:35], 0, v[64:65]
	v_lshl_add_u64 v[64:65], v[64:65], 0, v[2:3]
	v_add_f32_e32 v16, 1.0, v16
	v_rcp_f32_e32 v16, v16
	v_lshl_add_u64 v[8:9], v[8:9], 0, v[2:3]
	v_lshlrev_b64 v[6:7], 7, v[6:7]
	v_lshl_add_u64 v[6:7], s[34:35], 0, v[6:7]
	v_mul_f32_e32 v16, v32, v16
	v_bfe_u32 v32, v16, 16, 1
	v_add3_u32 v16, v16, v32, s63
	global_store_short_d16_hi v[64:65], v16, off nt
	v_lshlrev_b32_e32 v16, 16, v173
	v_mul_f32_e32 v32, v49, v166
	v_mul_f32_e32 v32, v32, v16
	v_mul_f32_e32 v16, 0xbfb8aa3b, v16
	v_exp_f32_e32 v16, v16
	v_lshl_add_u64 v[6:7], v[6:7], 0, v[2:3]
	v_lshlrev_b64 v[4:5], 7, v[4:5]
	v_lshl_add_u64 v[4:5], s[34:35], 0, v[4:5]
	v_add_f32_e32 v16, 1.0, v16
	v_rcp_f32_e32 v16, v16
	v_readlane_b32 s0, v254, 14
	s_add_i32 s76, s76, s66
	s_add_i32 s75, s75, s0
	v_mul_f32_e32 v16, v32, v16
	v_bfe_u32 v32, v16, 16, 1
	v_add3_u32 v16, v16, v32, s63
	global_store_short_d16_hi v[64:65], v16, off offset:64 nt
	s_waitcnt vmcnt(62)
	v_lshlrev_b32_e32 v16, 16, v172
	v_mul_f32_e32 v32, v33, v166
	v_mul_f32_e32 v32, v32, v16
	v_mul_f32_e32 v16, 0xbfb8aa3b, v16
	v_exp_f32_e32 v16, v16
	s_cmpk_gt_i32 s76, 0x3ff
	v_add_f32_e32 v16, 1.0, v16
	v_rcp_f32_e32 v16, v16
	s_nop 0
	v_mul_f32_e32 v16, v32, v16
	v_bfe_u32 v32, v16, 16, 1
	v_add3_u32 v16, v16, v32, s63
	v_add_co_u32_e32 v32, vcc, s93, v64
	s_nop 1
	v_addc_co_u32_e32 v33, vcc, 0, v65, vcc
	global_store_short_d16_hi v[32:33], v16, off nt
	v_lshlrev_b32_e32 v16, 16, v170
	v_mul_f32_e32 v17, v17, v16
	v_mul_f32_e32 v16, 0xbfb8aa3b, v16
	v_exp_f32_e32 v16, v16
	s_nop 0
	v_add_f32_e32 v16, 1.0, v16
	v_rcp_f32_e32 v16, v16
	s_nop 0
	v_mul_f32_e32 v16, v17, v16
	v_bfe_u32 v17, v16, 16, 1
	v_add3_u32 v16, v16, v17, s63
	global_store_short_d16_hi v[32:33], v16, off offset:64 nt
	s_waitcnt vmcnt(62)
	v_lshlrev_b32_e32 v16, 16, v169
	v_mul_f32_e32 v17, v66, v161
	v_mul_f32_e32 v17, v17, v16
	v_mul_f32_e32 v16, 0xbfb8aa3b, v16
	v_exp_f32_e32 v16, v16
	v_mul_f32_e32 v33, v50, v161
	v_add_f32_e32 v16, 1.0, v16
	v_rcp_f32_e32 v16, v16
	s_nop 0
	v_mul_f32_e32 v16, v17, v16
	v_bfe_u32 v17, v16, 16, 1
	v_add3_u32 v32, v16, v17, s63
	v_lshlrev_b64 v[16:17], 7, v[94:95]
	v_lshl_add_u64 v[16:17], s[34:35], 0, v[16:17]
	v_lshl_add_u64 v[16:17], v[16:17], 0, v[2:3]
	global_store_short_d16_hi v[16:17], v32, off nt
	v_lshlrev_b32_e32 v32, 16, v168
	v_mul_f32_e32 v33, v33, v32
	v_mul_f32_e32 v32, 0xbfb8aa3b, v32
	v_exp_f32_e32 v32, v32
	s_nop 0
	v_add_f32_e32 v32, 1.0, v32
	v_rcp_f32_e32 v32, v32
	s_nop 0
	v_mul_f32_e32 v32, v33, v32
	v_bfe_u32 v33, v32, 16, 1
	v_add3_u32 v32, v32, v33, s63
	global_store_short_d16_hi v[16:17], v32, off offset:64 nt
	s_waitcnt vmcnt(62)
	v_lshlrev_b32_e32 v32, 16, v167
	v_mul_f32_e32 v33, v34, v161
	v_mul_f32_e32 v33, v33, v32
	v_mul_f32_e32 v32, 0xbfb8aa3b, v32
	v_exp_f32_e32 v32, v32
	v_add_co_u32_e32 v16, vcc, s93, v16
	v_add_f32_e32 v32, 1.0, v32
	v_rcp_f32_e32 v32, v32
	v_addc_co_u32_e32 v17, vcc, 0, v17, vcc
	v_mul_f32_e32 v32, v33, v32
	v_bfe_u32 v33, v32, 16, 1
	v_add3_u32 v32, v32, v33, s63
	global_store_short_d16_hi v[16:17], v32, off nt
	v_lshlrev_b32_e32 v32, 16, v165
	v_mul_f32_e32 v18, v18, v32
	v_mul_f32_e32 v32, 0xbfb8aa3b, v32
	v_exp_f32_e32 v32, v32
	s_nop 0
	v_add_f32_e32 v32, 1.0, v32
	v_rcp_f32_e32 v32, v32
	s_nop 0
	v_mul_f32_e32 v18, v18, v32
	v_bfe_u32 v32, v18, 16, 1
	v_add3_u32 v18, v18, v32, s63
	global_store_short_d16_hi v[16:17], v18, off offset:64 nt
	s_waitcnt vmcnt(62)
; __device__ __forceinline__ float bf2f(unsigned h) { return __uint_as_float(h << 16); }
; __device__ __forceinline__ unsigned f2bf(float f) { unsigned u = __float_as_uint(f); return (u + 0x7fffu + ((u >> 16) & 1u)) >> 16; }
; __device__ __forceinline__ int crow(int r, int hi) { return (r & 3) + 8 * (r >> 2) + 4 * hi; }
; __device__ __forceinline__ void na_unit3(char* lds, const bf16_t* __restrict__ Qp, const bf16_t* __restrict__ Knp, const bf16_t* __restrict__ Vp, ...
;     ...
;     for (int r = 0; r < 16; ++r) { const long trow = wid * QBLK + crow(r, hi);
; #pragma unroll
;       for (int d0 = 0; d0 < 4; ++d0) { const float z = bf2f(zr[r][d0]); const float v = o[d0][r] * rli[r];
;         const float g = v * z * __builtin_amdgcn_rcpf(1.f + __expf(-z));
;         Op[((size_t)(d0 >> 1) * M_TOK + trow) * 64 + (d0 & 1) * 32 + r32] = (bf16_t)f2bf(g); } } }
	v_lshlrev_b32_e32 v16, 16, v164
	v_mul_f32_e32 v17, v67, v155
	v_mul_f32_e32 v17, v17, v16
	v_mul_f32_e32 v16, 0xbfb8aa3b, v16
	v_exp_f32_e32 v16, v16
	v_mul_f32_e32 v32, v51, v155
	v_add_f32_e32 v16, 1.0, v16
	v_rcp_f32_e32 v16, v16
	s_nop 0
	v_mul_f32_e32 v16, v17, v16
	v_bfe_u32 v17, v16, 16, 1
	v_add3_u32 v18, v16, v17, s63
	v_lshlrev_b64 v[16:17], 7, v[92:93]
	v_lshl_add_u64 v[16:17], s[34:35], 0, v[16:17]
	v_lshl_add_u64 v[16:17], v[16:17], 0, v[2:3]
	global_store_short_d16_hi v[16:17], v18, off nt
	v_lshlrev_b32_e32 v18, 16, v163
	v_mul_f32_e32 v32, v32, v18
	v_mul_f32_e32 v18, 0xbfb8aa3b, v18
	v_exp_f32_e32 v18, v18
	s_nop 0
	v_add_f32_e32 v18, 1.0, v18
	v_rcp_f32_e32 v18, v18
	s_nop 0
	v_mul_f32_e32 v18, v32, v18
	v_bfe_u32 v32, v18, 16, 1
	v_add3_u32 v18, v18, v32, s63
	global_store_short_d16_hi v[16:17], v18, off offset:64 nt
	s_waitcnt vmcnt(62)
	v_lshlrev_b32_e32 v18, 16, v162
	v_mul_f32_e32 v32, v35, v155
	v_mul_f32_e32 v32, v32, v18
	v_mul_f32_e32 v18, 0xbfb8aa3b, v18
	v_exp_f32_e32 v18, v18
	v_add_co_u32_e32 v16, vcc, s93, v16
	v_add_f32_e32 v18, 1.0, v18
	v_rcp_f32_e32 v18, v18
	v_addc_co_u32_e32 v17, vcc, 0, v17, vcc
	v_mul_f32_e32 v18, v32, v18
	v_bfe_u32 v32, v18, 16, 1
	v_add3_u32 v18, v18, v32, s63
	global_store_short_d16_hi v[16:17], v18, off nt
	v_lshlrev_b32_e32 v18, 16, v160
	v_mul_f32_e32 v19, v19, v18
	v_mul_f32_e32 v18, 0xbfb8aa3b, v18
	v_exp_f32_e32 v18, v18
	s_nop 0
	v_add_f32_e32 v18, 1.0, v18
	v_rcp_f32_e32 v18, v18
	s_nop 0
	v_mul_f32_e32 v18, v19, v18
	v_bfe_u32 v19, v18, 16, 1
	v_add3_u32 v18, v18, v19, s63
	global_store_short_d16_hi v[16:17], v18, off offset:64 nt
	s_waitcnt vmcnt(62)
	v_lshlrev_b32_e32 v16, 16, v159
	v_mul_f32_e32 v17, v68, v149
	v_mul_f32_e32 v17, v17, v16
	v_mul_f32_e32 v16, 0xbfb8aa3b, v16
	v_exp_f32_e32 v16, v16
	v_mul_f32_e32 v19, v52, v149
	v_add_f32_e32 v16, 1.0, v16
	v_rcp_f32_e32 v16, v16
	s_nop 0
	v_mul_f32_e32 v16, v17, v16
	v_bfe_u32 v17, v16, 16, 1
	v_add3_u32 v18, v16, v17, s63
	v_lshlrev_b64 v[16:17], 7, v[90:91]
	v_lshl_add_u64 v[16:17], s[34:35], 0, v[16:17]
	v_lshl_add_u64 v[16:17], v[16:17], 0, v[2:3]
	global_store_short_d16_hi v[16:17], v18, off nt
	v_lshlrev_b32_e32 v18, 16, v158
	v_mul_f32_e32 v19, v19, v18
	v_mul_f32_e32 v18, 0xbfb8aa3b, v18
	v_exp_f32_e32 v18, v18
	s_nop 0
	v_add_f32_e32 v18, 1.0, v18
	v_rcp_f32_e32 v18, v18
	s_nop 0
	v_mul_f32_e32 v18, v19, v18
	v_bfe_u32 v19, v18, 16, 1
	v_add3_u32 v18, v18, v19, s63
	global_store_short_d16_hi v[16:17], v18, off offset:64 nt
	s_waitcnt vmcnt(62)
	v_lshlrev_b32_e32 v18, 16, v157
	v_mul_f32_e32 v19, v36, v149
	v_mul_f32_e32 v19, v19, v18
	v_mul_f32_e32 v18, 0xbfb8aa3b, v18
	v_exp_f32_e32 v18, v18
	v_add_co_u32_e32 v16, vcc, s93, v16
	v_add_f32_e32 v18, 1.0, v18
	v_rcp_f32_e32 v18, v18
	v_addc_co_u32_e32 v17, vcc, 0, v17, vcc
	v_mul_f32_e32 v18, v19, v18
	v_bfe_u32 v19, v18, 16, 1
	v_add3_u32 v18, v18, v19, s63
	global_store_short_d16_hi v[16:17], v18, off nt
	v_lshlrev_b32_e32 v18, 16, v156
	v_mul_f32_e32 v19, v20, v149
	v_mul_f32_e32 v19, v19, v18
	v_mul_f32_e32 v18, 0xbfb8aa3b, v18
	v_exp_f32_e32 v18, v18
	s_nop 0
	v_add_f32_e32 v18, 1.0, v18
	v_rcp_f32_e32 v18, v18
	s_nop 0
	v_mul_f32_e32 v18, v19, v18
	v_bfe_u32 v19, v18, 16, 1
	v_add3_u32 v18, v18, v19, s63
	global_store_short_d16_hi v[16:17], v18, off offset:64 nt
	s_waitcnt vmcnt(62)
	v_lshlrev_b32_e32 v16, 16, v154
	v_mul_f32_e32 v17, v69, v144
	v_mul_f32_e32 v17, v17, v16
	v_mul_f32_e32 v16, 0xbfb8aa3b, v16
	v_exp_f32_e32 v16, v16
	v_mul_f32_e32 v19, v53, v144
	v_add_f32_e32 v16, 1.0, v16
	v_rcp_f32_e32 v16, v16
	s_nop 0
	v_mul_f32_e32 v16, v17, v16
	v_bfe_u32 v17, v16, 16, 1
	v_add3_u32 v18, v16, v17, s63
	v_lshlrev_b64 v[16:17], 7, v[88:89]
	v_lshl_add_u64 v[16:17], s[34:35], 0, v[16:17]
	v_lshl_add_u64 v[16:17], v[16:17], 0, v[2:3]
	global_store_short_d16_hi v[16:17], v18, off nt
	v_lshlrev_b32_e32 v18, 16, v153
	v_mul_f32_e32 v19, v19, v18
	v_mul_f32_e32 v18, 0xbfb8aa3b, v18
	v_exp_f32_e32 v18, v18
	s_nop 0
	v_add_f32_e32 v18, 1.0, v18
	v_rcp_f32_e32 v18, v18
	s_nop 0
	v_mul_f32_e32 v18, v19, v18
	v_bfe_u32 v19, v18, 16, 1
	v_add3_u32 v18, v18, v19, s63
	global_store_short_d16_hi v[16:17], v18, off offset:64 nt
	s_waitcnt vmcnt(62)
	v_lshlrev_b32_e32 v18, 16, v152
	v_mul_f32_e32 v19, v37, v144
	v_mul_f32_e32 v19, v19, v18
	v_mul_f32_e32 v18, 0xbfb8aa3b, v18
	v_exp_f32_e32 v18, v18
	v_add_co_u32_e32 v16, vcc, s93, v16
	v_add_f32_e32 v18, 1.0, v18
	v_rcp_f32_e32 v18, v18
	v_addc_co_u32_e32 v17, vcc, 0, v17, vcc
	v_mul_f32_e32 v18, v19, v18
	v_bfe_u32 v19, v18, 16, 1
	v_add3_u32 v18, v18, v19, s63
	global_store_short_d16_hi v[16:17], v18, off nt
	v_lshlrev_b32_e32 v18, 16, v151
	v_mul_f32_e32 v19, v21, v144
	v_mul_f32_e32 v19, v19, v18
	v_mul_f32_e32 v18, 0xbfb8aa3b, v18
	v_exp_f32_e32 v18, v18
	s_nop 0
	v_add_f32_e32 v18, 1.0, v18
	v_rcp_f32_e32 v18, v18
	s_nop 0
	v_mul_f32_e32 v18, v19, v18
	v_bfe_u32 v19, v18, 16, 1
	v_add3_u32 v18, v18, v19, s63
	global_store_short_d16_hi v[16:17], v18, off offset:64 nt
	s_waitcnt vmcnt(62)
	v_lshlrev_b32_e32 v16, 16, v150
	v_mul_f32_e32 v17, v70, v139
	v_mul_f32_e32 v17, v17, v16
	v_mul_f32_e32 v16, 0xbfb8aa3b, v16
	v_exp_f32_e32 v16, v16
	v_mul_f32_e32 v19, v54, v139
	v_add_f32_e32 v16, 1.0, v16
	v_rcp_f32_e32 v16, v16
	s_nop 0
	v_mul_f32_e32 v16, v17, v16
	v_bfe_u32 v17, v16, 16, 1
	v_add3_u32 v18, v16, v17, s63
	v_lshlrev_b64 v[16:17], 7, v[86:87]
	v_lshl_add_u64 v[16:17], s[34:35], 0, v[16:17]
	v_lshl_add_u64 v[16:17], v[16:17], 0, v[2:3]
	global_store_short_d16_hi v[16:17], v18, off nt
	v_lshlrev_b32_e32 v18, 16, v148
	v_mul_f32_e32 v19, v19, v18
	v_mul_f32_e32 v18, 0xbfb8aa3b, v18
	v_exp_f32_e32 v18, v18
	s_nop 0
	v_add_f32_e32 v18, 1.0, v18
	v_rcp_f32_e32 v18, v18
	s_nop 0
	v_mul_f32_e32 v18, v19, v18
	v_bfe_u32 v19, v18, 16, 1
	v_add3_u32 v18, v18, v19, s63
	global_store_short_d16_hi v[16:17], v18, off offset:64 nt
	s_waitcnt vmcnt(62)
; __device__ __forceinline__ float bf2f(unsigned h) { return __uint_as_float(h << 16); }
; __device__ __forceinline__ unsigned f2bf(float f) { unsigned u = __float_as_uint(f); return (u + 0x7fffu + ((u >> 16) & 1u)) >> 16; }
; __device__ __forceinline__ int crow(int r, int hi) { return (r & 3) + 8 * (r >> 2) + 4 * hi; }
; __device__ __forceinline__ void na_unit3(char* lds, const bf16_t* __restrict__ Qp, const bf16_t* __restrict__ Knp, const bf16_t* __restrict__ Vp, ...
;     ...
;     for (int r = 0; r < 16; ++r) { const long trow = wid * QBLK + crow(r, hi);
; #pragma unroll
;       for (int d0 = 0; d0 < 4; ++d0) { const float z = bf2f(zr[r][d0]); const float v = o[d0][r] * rli[r];
;         const float g = v * z * __builtin_amdgcn_rcpf(1.f + __expf(-z));
;         Op[((size_t)(d0 >> 1) * M_TOK + trow) * 64 + (d0 & 1) * 32 + r32] = (bf16_t)f2bf(g); } } }
	v_lshlrev_b32_e32 v18, 16, v147
	v_mul_f32_e32 v19, v38, v139
	v_mul_f32_e32 v19, v19, v18
	v_mul_f32_e32 v18, 0xbfb8aa3b, v18
	v_exp_f32_e32 v18, v18
	v_add_co_u32_e32 v16, vcc, s93, v16
	v_add_f32_e32 v18, 1.0, v18
	v_rcp_f32_e32 v18, v18
	v_addc_co_u32_e32 v17, vcc, 0, v17, vcc
	v_mul_f32_e32 v18, v19, v18
	v_bfe_u32 v19, v18, 16, 1
	v_add3_u32 v18, v18, v19, s63
	global_store_short_d16_hi v[16:17], v18, off nt
	v_lshlrev_b32_e32 v18, 16, v146
	v_mul_f32_e32 v19, v22, v139
	v_mul_f32_e32 v19, v19, v18
	v_mul_f32_e32 v18, 0xbfb8aa3b, v18
	v_exp_f32_e32 v18, v18
	s_nop 0
	v_add_f32_e32 v18, 1.0, v18
	v_rcp_f32_e32 v18, v18
	s_nop 0
	v_mul_f32_e32 v18, v19, v18
	v_bfe_u32 v19, v18, 16, 1
	v_add3_u32 v18, v18, v19, s63
	global_store_short_d16_hi v[16:17], v18, off offset:64 nt
	s_waitcnt vmcnt(62)
	v_lshlrev_b32_e32 v16, 16, v145
	v_mul_f32_e32 v17, v71, v133
	v_mul_f32_e32 v17, v17, v16
	v_mul_f32_e32 v16, 0xbfb8aa3b, v16
	v_exp_f32_e32 v16, v16
	v_mul_f32_e32 v19, v55, v133
	v_add_f32_e32 v16, 1.0, v16
	v_rcp_f32_e32 v16, v16
	s_nop 0
	v_mul_f32_e32 v16, v17, v16
	v_bfe_u32 v17, v16, 16, 1
	v_add3_u32 v18, v16, v17, s63
	v_lshlrev_b64 v[16:17], 7, v[84:85]
	v_lshl_add_u64 v[16:17], s[34:35], 0, v[16:17]
	v_lshl_add_u64 v[16:17], v[16:17], 0, v[2:3]
	global_store_short_d16_hi v[16:17], v18, off nt
	v_lshlrev_b32_e32 v18, 16, v143
	v_mul_f32_e32 v19, v19, v18
	v_mul_f32_e32 v18, 0xbfb8aa3b, v18
	v_exp_f32_e32 v18, v18
	s_nop 0
	v_add_f32_e32 v18, 1.0, v18
	v_rcp_f32_e32 v18, v18
	s_nop 0
	v_mul_f32_e32 v18, v19, v18
	v_bfe_u32 v19, v18, 16, 1
	v_add3_u32 v18, v18, v19, s63
	global_store_short_d16_hi v[16:17], v18, off offset:64 nt
	s_waitcnt vmcnt(62)
	v_lshlrev_b32_e32 v18, 16, v142
	v_mul_f32_e32 v19, v39, v133
	v_mul_f32_e32 v19, v19, v18
	v_mul_f32_e32 v18, 0xbfb8aa3b, v18
	v_exp_f32_e32 v18, v18
	v_add_co_u32_e32 v16, vcc, s93, v16
	v_add_f32_e32 v18, 1.0, v18
	v_rcp_f32_e32 v18, v18
	v_addc_co_u32_e32 v17, vcc, 0, v17, vcc
	v_mul_f32_e32 v18, v19, v18
	v_bfe_u32 v19, v18, 16, 1
	v_add3_u32 v18, v18, v19, s63
	global_store_short_d16_hi v[16:17], v18, off nt
	v_lshlrev_b32_e32 v18, 16, v141
	v_mul_f32_e32 v19, v23, v133
	v_mul_f32_e32 v19, v19, v18
	v_mul_f32_e32 v18, 0xbfb8aa3b, v18
	v_exp_f32_e32 v18, v18
	s_nop 0
	v_add_f32_e32 v18, 1.0, v18
	v_rcp_f32_e32 v18, v18
	s_nop 0
	v_mul_f32_e32 v18, v19, v18
	v_bfe_u32 v19, v18, 16, 1
	v_add3_u32 v18, v18, v19, s63
	global_store_short_d16_hi v[16:17], v18, off offset:64 nt
	s_waitcnt vmcnt(62)
	v_lshlrev_b32_e32 v16, 16, v140
	v_mul_f32_e32 v17, v72, v128
	v_mul_f32_e32 v17, v17, v16
	v_mul_f32_e32 v16, 0xbfb8aa3b, v16
	v_exp_f32_e32 v16, v16
	v_mul_f32_e32 v19, v56, v128
	v_add_f32_e32 v16, 1.0, v16
	v_rcp_f32_e32 v16, v16
	s_nop 0
	v_mul_f32_e32 v16, v17, v16
	v_bfe_u32 v17, v16, 16, 1
	v_add3_u32 v18, v16, v17, s63
	v_lshlrev_b64 v[16:17], 7, v[82:83]
	v_lshl_add_u64 v[16:17], s[34:35], 0, v[16:17]
	v_lshl_add_u64 v[16:17], v[16:17], 0, v[2:3]
	global_store_short_d16_hi v[16:17], v18, off nt
	v_lshlrev_b32_e32 v18, 16, v138
	v_mul_f32_e32 v19, v19, v18
	v_mul_f32_e32 v18, 0xbfb8aa3b, v18
	v_exp_f32_e32 v18, v18
	s_nop 0
	v_add_f32_e32 v18, 1.0, v18
	v_rcp_f32_e32 v18, v18
	s_nop 0
	v_mul_f32_e32 v18, v19, v18
	v_bfe_u32 v19, v18, 16, 1
	v_add3_u32 v18, v18, v19, s63
	global_store_short_d16_hi v[16:17], v18, off offset:64 nt
	s_waitcnt vmcnt(62)
	v_lshlrev_b32_e32 v18, 16, v137
	v_mul_f32_e32 v19, v40, v128
	v_mul_f32_e32 v19, v19, v18
	v_mul_f32_e32 v18, 0xbfb8aa3b, v18
	v_exp_f32_e32 v18, v18
	v_add_co_u32_e32 v16, vcc, s93, v16
	v_add_f32_e32 v18, 1.0, v18
	v_rcp_f32_e32 v18, v18
	v_addc_co_u32_e32 v17, vcc, 0, v17, vcc
	v_mul_f32_e32 v18, v19, v18
	v_bfe_u32 v19, v18, 16, 1
	v_add3_u32 v18, v18, v19, s63
	global_store_short_d16_hi v[16:17], v18, off nt
	v_lshlrev_b32_e32 v18, 16, v136
	v_mul_f32_e32 v19, v24, v128
	v_mul_f32_e32 v19, v19, v18
	v_mul_f32_e32 v18, 0xbfb8aa3b, v18
	v_exp_f32_e32 v18, v18
	s_nop 0
	v_add_f32_e32 v18, 1.0, v18
	v_rcp_f32_e32 v18, v18
	s_nop 0
	v_mul_f32_e32 v18, v19, v18
	v_bfe_u32 v19, v18, 16, 1
	v_add3_u32 v18, v18, v19, s63
	global_store_short_d16_hi v[16:17], v18, off offset:64 nt
	s_waitcnt vmcnt(62)
	v_lshlrev_b32_e32 v16, 16, v135
	v_mul_f32_e32 v17, v73, v122
	v_mul_f32_e32 v17, v17, v16
	v_mul_f32_e32 v16, 0xbfb8aa3b, v16
	v_exp_f32_e32 v16, v16
	v_mul_f32_e32 v19, v57, v122
	v_add_f32_e32 v16, 1.0, v16
	v_rcp_f32_e32 v16, v16
	s_nop 0
	v_mul_f32_e32 v16, v17, v16
	v_bfe_u32 v17, v16, 16, 1
	v_add3_u32 v18, v16, v17, s63
	v_lshlrev_b64 v[16:17], 7, v[80:81]
	v_lshl_add_u64 v[16:17], s[34:35], 0, v[16:17]
	v_lshl_add_u64 v[16:17], v[16:17], 0, v[2:3]
	global_store_short_d16_hi v[16:17], v18, off nt
	v_lshlrev_b32_e32 v18, 16, v134
	v_mul_f32_e32 v19, v19, v18
	v_mul_f32_e32 v18, 0xbfb8aa3b, v18
	v_exp_f32_e32 v18, v18
	v_lshl_add_u64 v[2:3], v[4:5], 0, v[2:3]
	s_waitcnt vmcnt(39)
	v_lshlrev_b32_e32 v4, 16, v104
	v_mul_f32_e32 v5, v63, v1
	v_add_f32_e32 v18, 1.0, v18
	v_rcp_f32_e32 v18, v18
	v_mul_f32_e32 v5, v5, v4
	v_mul_f32_e32 v4, 0xbfb8aa3b, v4
	v_exp_f32_e32 v4, v4
	v_mul_f32_e32 v18, v19, v18
	v_bfe_u32 v19, v18, 16, 1
	v_add3_u32 v18, v18, v19, s63
	global_store_short_d16_hi v[16:17], v18, off offset:64 nt
	v_lshlrev_b32_e32 v18, 16, v132
	v_mul_f32_e32 v19, v41, v122
	v_mul_f32_e32 v19, v19, v18
	v_mul_f32_e32 v18, 0xbfb8aa3b, v18
	v_exp_f32_e32 v18, v18
	v_add_co_u32_e32 v16, vcc, s93, v16
	v_add_f32_e32 v4, 1.0, v4
	v_add_f32_e32 v18, 1.0, v18
	v_rcp_f32_e32 v18, v18
	v_addc_co_u32_e32 v17, vcc, 0, v17, vcc
	v_rcp_f32_e32 v4, v4
	v_mul_f32_e32 v18, v19, v18
	v_bfe_u32 v19, v18, 16, 1
	v_add3_u32 v18, v18, v19, s63
	global_store_short_d16_hi v[16:17], v18, off nt
	v_lshlrev_b32_e32 v18, 16, v131
	v_mul_f32_e32 v19, v25, v122
	v_mul_f32_e32 v19, v19, v18
	v_mul_f32_e32 v18, 0xbfb8aa3b, v18
	v_exp_f32_e32 v18, v18
	v_mul_f32_e32 v4, v5, v4
	v_bfe_u32 v5, v4, 16, 1
	v_add3_u32 v4, v4, v5, s63
	v_add_f32_e32 v18, 1.0, v18
	v_rcp_f32_e32 v18, v18
	global_store_short_d16_hi v[2:3], v4, off offset:64 nt
	s_waitcnt vmcnt(41)
; __device__ __forceinline__ float bf2f(unsigned h) { return __uint_as_float(h << 16); }
; __device__ __forceinline__ unsigned f2bf(float f) { unsigned u = __float_as_uint(f); return (u + 0x7fffu + ((u >> 16) & 1u)) >> 16; }
; __device__ __forceinline__ int crow(int r, int hi) { return (r & 3) + 8 * (r >> 2) + 4 * hi; }
; __device__ __forceinline__ void na_unit3(char* lds, const bf16_t* __restrict__ Qp, const bf16_t* __restrict__ Knp, const bf16_t* __restrict__ Vp, ...
;     ...
;     for (int r = 0; r < 16; ++r) { const long trow = wid * QBLK + crow(r, hi);
; #pragma unroll
;       for (int d0 = 0; d0 < 4; ++d0) { const float z = bf2f(zr[r][d0]); const float v = o[d0][r] * rli[r];
;         const float g = v * z * __builtin_amdgcn_rcpf(1.f + __expf(-z));
;         Op[((size_t)(d0 >> 1) * M_TOK + trow) * 64 + (d0 & 1) * 32 + r32] = (bf16_t)f2bf(g); } } }
	v_lshlrev_b32_e32 v4, 16, v101
	v_mul_f32_e32 v5, v47, v1
	v_mul_f32_e32 v18, v19, v18
	v_bfe_u32 v19, v18, 16, 1
	v_add3_u32 v18, v18, v19, s63
	global_store_short_d16_hi v[16:17], v18, off offset:64 nt
	v_lshlrev_b32_e32 v16, 16, v130
	v_mul_f32_e32 v17, v74, v117
	v_mul_f32_e32 v17, v17, v16
	v_mul_f32_e32 v16, 0xbfb8aa3b, v16
	v_exp_f32_e32 v16, v16
	v_mul_f32_e32 v5, v5, v4
	v_mul_f32_e32 v4, 0xbfb8aa3b, v4
	v_exp_f32_e32 v4, v4
	v_add_f32_e32 v16, 1.0, v16
	v_rcp_f32_e32 v16, v16
	v_add_f32_e32 v4, 1.0, v4
	v_rcp_f32_e32 v4, v4
	v_mul_f32_e32 v16, v17, v16
	v_bfe_u32 v17, v16, 16, 1
	v_add3_u32 v16, v16, v17, s63
	global_store_short_d16_hi v[14:15], v16, off nt
	v_lshlrev_b32_e32 v16, 16, v129
	v_mul_f32_e32 v17, v58, v117
	v_mul_f32_e32 v17, v17, v16
	v_mul_f32_e32 v16, 0xbfb8aa3b, v16
	v_exp_f32_e32 v16, v16
	v_mul_f32_e32 v4, v5, v4
	v_bfe_u32 v5, v4, 16, 1
	v_add3_u32 v4, v4, v5, s63
	v_add_f32_e32 v16, 1.0, v16
	v_rcp_f32_e32 v16, v16
	s_nop 0
	v_mul_f32_e32 v16, v17, v16
	v_bfe_u32 v17, v16, 16, 1
	v_add3_u32 v16, v16, v17, s63
	global_store_short_d16_hi v[14:15], v16, off offset:64 nt
	v_lshlrev_b32_e32 v16, 16, v127
	v_mul_f32_e32 v17, v42, v117
	v_mul_f32_e32 v17, v17, v16
	v_mul_f32_e32 v16, 0xbfb8aa3b, v16
	v_exp_f32_e32 v16, v16
	v_add_co_u32_e32 v14, vcc, s93, v14
	v_add_f32_e32 v16, 1.0, v16
	v_rcp_f32_e32 v16, v16
	v_addc_co_u32_e32 v15, vcc, 0, v15, vcc
	v_mul_f32_e32 v16, v17, v16
	v_bfe_u32 v17, v16, 16, 1
	v_add3_u32 v16, v16, v17, s63
	global_store_short_d16_hi v[14:15], v16, off nt
	v_lshlrev_b32_e32 v16, 16, v126
	v_mul_f32_e32 v17, v26, v117
	v_mul_f32_e32 v17, v17, v16
	v_mul_f32_e32 v16, 0xbfb8aa3b, v16
	v_exp_f32_e32 v16, v16
	s_nop 0
	v_add_f32_e32 v16, 1.0, v16
	v_rcp_f32_e32 v16, v16
	s_nop 0
	v_mul_f32_e32 v16, v17, v16
	v_bfe_u32 v17, v16, 16, 1
	v_add3_u32 v16, v16, v17, s63
	global_store_short_d16_hi v[14:15], v16, off offset:64 nt
	v_lshlrev_b32_e32 v14, 16, v125
	v_mul_f32_e32 v15, v75, v111
	v_mul_f32_e32 v15, v15, v14
	v_mul_f32_e32 v14, 0xbfb8aa3b, v14
	v_exp_f32_e32 v14, v14
	s_nop 0
	v_add_f32_e32 v14, 1.0, v14
	v_rcp_f32_e32 v14, v14
	s_nop 0
	v_mul_f32_e32 v14, v15, v14
	v_bfe_u32 v15, v14, 16, 1
	v_add3_u32 v14, v14, v15, s63
	global_store_short_d16_hi v[12:13], v14, off nt
	v_lshlrev_b32_e32 v14, 16, v124
	v_mul_f32_e32 v15, v59, v111
	v_mul_f32_e32 v15, v15, v14
	v_mul_f32_e32 v14, 0xbfb8aa3b, v14
	v_exp_f32_e32 v14, v14
	s_nop 0
	v_add_f32_e32 v14, 1.0, v14
	v_rcp_f32_e32 v14, v14
	s_nop 0
	v_mul_f32_e32 v14, v15, v14
	v_bfe_u32 v15, v14, 16, 1
	v_add3_u32 v14, v14, v15, s63
	global_store_short_d16_hi v[12:13], v14, off offset:64 nt
	v_lshlrev_b32_e32 v14, 16, v123
	v_mul_f32_e32 v15, v43, v111
	v_mul_f32_e32 v15, v15, v14
	v_mul_f32_e32 v14, 0xbfb8aa3b, v14
	v_exp_f32_e32 v14, v14
	v_add_co_u32_e32 v12, vcc, s93, v12
	v_add_f32_e32 v14, 1.0, v14
	v_rcp_f32_e32 v14, v14
	v_addc_co_u32_e32 v13, vcc, 0, v13, vcc
	v_mul_f32_e32 v14, v15, v14
	v_bfe_u32 v15, v14, 16, 1
	v_add3_u32 v14, v14, v15, s63
	global_store_short_d16_hi v[12:13], v14, off nt
	v_lshlrev_b32_e32 v14, 16, v121
	v_mul_f32_e32 v15, v27, v111
	v_mul_f32_e32 v15, v15, v14
	v_mul_f32_e32 v14, 0xbfb8aa3b, v14
	v_exp_f32_e32 v14, v14
	s_nop 0
	v_add_f32_e32 v14, 1.0, v14
	v_rcp_f32_e32 v14, v14
	s_nop 0
	v_mul_f32_e32 v14, v15, v14
	v_bfe_u32 v15, v14, 16, 1
	v_add3_u32 v14, v14, v15, s63
	global_store_short_d16_hi v[12:13], v14, off offset:64 nt
	v_lshlrev_b32_e32 v12, 16, v120
	v_mul_f32_e32 v13, v76, v105
	v_mul_f32_e32 v13, v13, v12
	v_mul_f32_e32 v12, 0xbfb8aa3b, v12
	v_exp_f32_e32 v12, v12
	s_nop 0
	v_add_f32_e32 v12, 1.0, v12
	v_rcp_f32_e32 v12, v12
	s_nop 0
	v_mul_f32_e32 v12, v13, v12
	v_bfe_u32 v13, v12, 16, 1
	v_add3_u32 v12, v12, v13, s63
	global_store_short_d16_hi v[10:11], v12, off nt
	v_lshlrev_b32_e32 v12, 16, v119
	v_mul_f32_e32 v13, v60, v105
	v_mul_f32_e32 v13, v13, v12
	v_mul_f32_e32 v12, 0xbfb8aa3b, v12
	v_exp_f32_e32 v12, v12
	s_nop 0
	v_add_f32_e32 v12, 1.0, v12
	v_rcp_f32_e32 v12, v12
	s_nop 0
	v_mul_f32_e32 v12, v13, v12
	v_bfe_u32 v13, v12, 16, 1
	v_add3_u32 v12, v12, v13, s63
	global_store_short_d16_hi v[10:11], v12, off offset:64 nt
	v_lshlrev_b32_e32 v12, 16, v118
	v_mul_f32_e32 v13, v44, v105
	v_mul_f32_e32 v13, v13, v12
	v_mul_f32_e32 v12, 0xbfb8aa3b, v12
	v_exp_f32_e32 v12, v12
	v_add_co_u32_e32 v10, vcc, s93, v10
	v_add_f32_e32 v12, 1.0, v12
; __device__ __forceinline__ float bf2f(unsigned h) { return __uint_as_float(h << 16); }
; __device__ __forceinline__ unsigned f2bf(float f) { unsigned u = __float_as_uint(f); return (u + 0x7fffu + ((u >> 16) & 1u)) >> 16; }
; #define SBAR() __builtin_amdgcn_sched_barrier(0)
; __device__ __forceinline__ int crow(int r, int hi) { return (r & 3) + 8 * (r >> 2) + 4 * hi; }
; __device__ __forceinline__ void na_unit3(char* lds, const bf16_t* __restrict__ Qp, const bf16_t* __restrict__ Knp, const bf16_t* __restrict__ Vp, ...
;     ...
;   { unsigned zr[16][4];
; #pragma unroll
;     for (int r = 0; r < 16; ++r) { const long trow = wid * QBLK + crow(r, hi);
; #pragma unroll
;       for (int d0 = 0; d0 < 4; ++d0) zr[r][d0] = Zp[trow * LDZ + d0 * 32 + r32]; }
;     asm volatile("s_waitcnt vmcnt(0)" ::: "memory"); SBAR();
; #pragma unroll
;     for (int r = 0; r < 16; ++r) { const long trow = wid * QBLK + crow(r, hi);
; #pragma unroll
;       for (int d0 = 0; d0 < 4; ++d0) { const float z = bf2f(zr[r][d0]); const float v = o[d0][r] * rli[r];
;         const float g = v * z * __builtin_amdgcn_rcpf(1.f + __expf(-z));
;         Op[((size_t)(d0 >> 1) * M_TOK + trow) * 64 + (d0 & 1) * 32 + r32] = (bf16_t)f2bf(g); } } }
;   asm volatile("s_waitcnt vmcnt(0) lgkmcnt(0)\n\ts_barrier" ::: "memory");
	v_rcp_f32_e32 v12, v12
	v_addc_co_u32_e32 v11, vcc, 0, v11, vcc
	v_mul_f32_e32 v12, v13, v12
	v_bfe_u32 v13, v12, 16, 1
	v_add3_u32 v12, v12, v13, s63
	global_store_short_d16_hi v[10:11], v12, off nt
	v_lshlrev_b32_e32 v12, 16, v116
	v_mul_f32_e32 v13, v28, v105
	v_mul_f32_e32 v13, v13, v12
	v_mul_f32_e32 v12, 0xbfb8aa3b, v12
	v_exp_f32_e32 v12, v12
	s_nop 0
	v_add_f32_e32 v12, 1.0, v12
	v_rcp_f32_e32 v12, v12
	s_nop 0
	v_mul_f32_e32 v12, v13, v12
	v_bfe_u32 v13, v12, 16, 1
	v_add3_u32 v12, v12, v13, s63
	global_store_short_d16_hi v[10:11], v12, off offset:64 nt
	v_lshlrev_b32_e32 v10, 16, v115
	v_mul_f32_e32 v11, v77, v103
	v_mul_f32_e32 v11, v11, v10
	v_mul_f32_e32 v10, 0xbfb8aa3b, v10
	v_exp_f32_e32 v10, v10
	s_nop 0
	v_add_f32_e32 v10, 1.0, v10
	v_rcp_f32_e32 v10, v10
	s_nop 0
	v_mul_f32_e32 v10, v11, v10
	v_bfe_u32 v11, v10, 16, 1
	v_add3_u32 v10, v10, v11, s63
	global_store_short_d16_hi v[8:9], v10, off nt
	v_lshlrev_b32_e32 v10, 16, v114
	v_mul_f32_e32 v11, v61, v103
	v_mul_f32_e32 v11, v11, v10
	v_mul_f32_e32 v10, 0xbfb8aa3b, v10
	v_exp_f32_e32 v10, v10
	s_nop 0
	v_add_f32_e32 v10, 1.0, v10
	v_rcp_f32_e32 v10, v10
	s_nop 0
	v_mul_f32_e32 v10, v11, v10
	v_bfe_u32 v11, v10, 16, 1
	v_add3_u32 v10, v10, v11, s63
	global_store_short_d16_hi v[8:9], v10, off offset:64 nt
	v_lshlrev_b32_e32 v10, 16, v113
	v_mul_f32_e32 v11, v45, v103
	v_mul_f32_e32 v11, v11, v10
	v_mul_f32_e32 v10, 0xbfb8aa3b, v10
	v_exp_f32_e32 v10, v10
	v_add_co_u32_e32 v8, vcc, s93, v8
	v_add_f32_e32 v10, 1.0, v10
	v_rcp_f32_e32 v10, v10
	v_addc_co_u32_e32 v9, vcc, 0, v9, vcc
	v_mul_f32_e32 v10, v11, v10
	v_bfe_u32 v11, v10, 16, 1
	v_add3_u32 v10, v10, v11, s63
	global_store_short_d16_hi v[8:9], v10, off nt
	v_lshlrev_b32_e32 v10, 16, v112
	v_mul_f32_e32 v11, v29, v103
	v_mul_f32_e32 v11, v11, v10
	v_mul_f32_e32 v10, 0xbfb8aa3b, v10
	v_exp_f32_e32 v10, v10
	s_nop 0
	v_add_f32_e32 v10, 1.0, v10
	v_rcp_f32_e32 v10, v10
	s_nop 0
	v_mul_f32_e32 v10, v11, v10
	v_bfe_u32 v11, v10, 16, 1
	v_add3_u32 v10, v10, v11, s63
	global_store_short_d16_hi v[8:9], v10, off offset:64 nt
	v_lshlrev_b32_e32 v8, 16, v110
	v_mul_f32_e32 v9, v78, v102
	v_mul_f32_e32 v9, v9, v8
	v_mul_f32_e32 v8, 0xbfb8aa3b, v8
	v_exp_f32_e32 v8, v8
	s_nop 0
	v_add_f32_e32 v8, 1.0, v8
	v_rcp_f32_e32 v8, v8
	s_nop 0
	v_mul_f32_e32 v8, v9, v8
	v_bfe_u32 v9, v8, 16, 1
	v_add3_u32 v8, v8, v9, s63
	global_store_short_d16_hi v[6:7], v8, off nt
	v_lshlrev_b32_e32 v8, 16, v109
	v_mul_f32_e32 v9, v62, v102
	v_mul_f32_e32 v9, v9, v8
	v_mul_f32_e32 v8, 0xbfb8aa3b, v8
	v_exp_f32_e32 v8, v8
	s_nop 0
	v_add_f32_e32 v8, 1.0, v8
	v_rcp_f32_e32 v8, v8
	s_nop 0
	v_mul_f32_e32 v8, v9, v8
	v_bfe_u32 v9, v8, 16, 1
	v_add3_u32 v8, v8, v9, s63
	global_store_short_d16_hi v[6:7], v8, off offset:64 nt
	v_lshlrev_b32_e32 v8, 16, v108
	v_mul_f32_e32 v9, v46, v102
	v_mul_f32_e32 v9, v9, v8
	v_mul_f32_e32 v8, 0xbfb8aa3b, v8
	v_exp_f32_e32 v8, v8
	v_add_co_u32_e32 v6, vcc, s93, v6
	v_add_f32_e32 v8, 1.0, v8
	v_rcp_f32_e32 v8, v8
	v_addc_co_u32_e32 v7, vcc, 0, v7, vcc
	v_mul_f32_e32 v8, v9, v8
	v_bfe_u32 v9, v8, 16, 1
	v_add3_u32 v8, v8, v9, s63
	global_store_short_d16_hi v[6:7], v8, off nt
	v_lshlrev_b32_e32 v8, 16, v107
	v_mul_f32_e32 v9, v30, v102
	v_mul_f32_e32 v9, v9, v8
	v_mul_f32_e32 v8, 0xbfb8aa3b, v8
	v_exp_f32_e32 v8, v8
	s_nop 0
	v_add_f32_e32 v8, 1.0, v8
	v_rcp_f32_e32 v8, v8
	s_nop 0
	v_mul_f32_e32 v8, v9, v8
	v_bfe_u32 v9, v8, 16, 1
	v_add3_u32 v8, v8, v9, s63
	global_store_short_d16_hi v[6:7], v8, off offset:64 nt
	v_lshlrev_b32_e32 v6, 16, v106
	v_mul_f32_e32 v7, v79, v1
	v_mul_f32_e32 v7, v7, v6
	v_mul_f32_e32 v6, 0xbfb8aa3b, v6
	v_exp_f32_e32 v6, v6
	v_mul_f32_e32 v1, v31, v1
	v_add_f32_e32 v6, 1.0, v6
	v_rcp_f32_e32 v6, v6
	s_nop 0
	v_mul_f32_e32 v6, v7, v6
	v_bfe_u32 v7, v6, 16, 1
	v_add3_u32 v6, v6, v7, s63
	global_store_short_d16_hi v[2:3], v6, off nt
	v_add_co_u32_e32 v2, vcc, s93, v2
	s_nop 1
	v_addc_co_u32_e32 v3, vcc, 0, v3, vcc
	global_store_short_d16_hi v[2:3], v4, off nt
	s_waitcnt vmcnt(62)
	v_lshlrev_b32_e32 v4, 16, v100
	v_mul_f32_e32 v1, v1, v4
	v_mul_f32_e32 v4, 0xbfb8aa3b, v4
	v_exp_f32_e32 v4, v4
	s_nop 0
	v_add_f32_e32 v4, 1.0, v4
	v_rcp_f32_e32 v4, v4
	s_nop 0
	v_mul_f32_e32 v1, v1, v4
	v_bfe_u32 v4, v1, 16, 1
	v_add3_u32 v1, v1, v4, s63
	global_store_short_d16_hi v[2:3], v1, off offset:64 nt
	s_waitcnt vmcnt(0) lgkmcnt(0)
	s_barrier
	s_cbranch_scc1 .LBB0_352
